# nsa_ranking_stops_at_last_valid_block
# speedup vs baseline: 1.0132x; 1.0084x over previous
.LBB0_579:
	s_or_b64 exec, exec, s[2:3]
	v_add_u32_e32 v43, s14, v41
	s_waitcnt lgkmcnt(0)
	v_add_f32_e32 v32, v32, v33
	v_ashrrev_i32_e32 v43, 6, v43
	v_add_f32_e32 v32, v32, v34
	v_add_u32_e32 v44, -1, v43
	v_fmac_f32_e32 v32, 0.5, v35
	v_cmp_eq_u32_e64 s[0:1], v38, v43
	v_add_f32_e32 v32, v32, v42
	s_or_b64 s[0:1], vcc, s[0:1]
	v_cmp_eq_u32_e32 vcc, v38, v44
	v_add_f32_e32 v33, 0x447a0000, v32
	s_or_b64 vcc, s[0:1], vcc
	v_lshlrev_b32_e32 v41, 8, v41
	v_cndmask_b32_e32 v32, v32, v33, vcc
	v_cmp_le_i32_e32 vcc, v38, v43
	v_lshlrev_b32_e32 v33, 2, v38
	v_readlane_b32 s2, v254, 8
	v_or_b32_e32 v42, 16, v38
	v_cndmask_b32_e32 v32, -1.0, v32, vcc
	v_add3_u32 v41, s2, v41, v33
	v_lshl_add_u32 v45, v42, 4, v40
	ds_write_b32 v41, v32
	v_add_u32_e32 v32, -4, v45
	ds_read2_b32 v[32:33], v32 offset1:1
	ds_read2_b32 v[34:35], v45 offset0:1 offset1:2
	ds_read_b32 v45, v45 offset:12
	v_cmp_eq_u32_e32 vcc, v42, v43
	v_cmp_eq_u32_e64 s[0:1], v42, v44
	s_or_b64 vcc, vcc, s[0:1]
	s_waitcnt lgkmcnt(1)
	v_add_f32_e32 v33, v33, v34
	v_add_f32_e32 v33, v33, v35
	s_waitcnt lgkmcnt(0)
	v_fmac_f32_e32 v33, 0.5, v45
	v_fmac_f32_e32 v33, 0.5, v32
	v_add_f32_e32 v32, 0x447a0000, v33
	v_cndmask_b32_e32 v32, v33, v32, vcc
	v_cmp_le_i32_e32 vcc, v42, v43
	v_or_b32_e32 v42, 32, v38
	v_lshl_add_u32 v45, v42, 4, v40
	v_cndmask_b32_e32 v32, -1.0, v32, vcc
	ds_write_b32 v41, v32 offset:64
	v_add_u32_e32 v32, -4, v45
	ds_read2_b32 v[32:33], v32 offset1:1
	ds_read2_b32 v[34:35], v45 offset0:1 offset1:2
	ds_read_b32 v45, v45 offset:12
	v_cmp_eq_u32_e32 vcc, v42, v43
	v_cmp_eq_u32_e64 s[0:1], v42, v44
	s_or_b64 vcc, vcc, s[0:1]
	s_waitcnt lgkmcnt(1)
	v_add_f32_e32 v33, v33, v34
	v_add_f32_e32 v33, v33, v35
	s_waitcnt lgkmcnt(0)
	v_fmac_f32_e32 v33, 0.5, v45
	v_fmac_f32_e32 v33, 0.5, v32
	v_add_f32_e32 v32, 0x447a0000, v33
	v_cndmask_b32_e32 v32, v33, v32, vcc
	v_cmp_le_i32_e32 vcc, v42, v43
	v_or_b32_e32 v42, 48, v38
	v_lshl_add_u32 v40, v42, 4, v40
	v_cndmask_b32_e32 v32, -1.0, v32, vcc
	ds_write_b32 v41, v32 offset:128
	v_add_u32_e32 v32, -4, v40
	ds_read2_b32 v[32:33], v32 offset1:1
	ds_read2_b32 v[34:35], v40 offset0:1 offset1:2
	ds_read_b32 v40, v40 offset:12
	v_cmp_eq_u32_e32 vcc, v42, v43
	v_cmp_eq_u32_e64 s[0:1], v42, v44
	s_or_b64 vcc, vcc, s[0:1]
	s_waitcnt lgkmcnt(1)
	v_add_f32_e32 v33, v33, v34
	v_add_f32_e32 v33, v33, v35
	s_waitcnt lgkmcnt(0)
	v_fmac_f32_e32 v33, 0.5, v40
	v_fmac_f32_e32 v33, 0.5, v32
	v_add_f32_e32 v32, 0x447a0000, v33
	v_cndmask_b32_e32 v32, v33, v32, vcc
	v_cmp_le_i32_e32 vcc, v42, v43
	s_lshl_b32 s0, s15, 8
	s_add_i32 s0, s2, s0
	v_cndmask_b32_e32 v32, -1.0, v32, vcc
	s_or_b32 s12, s15, 2
	ds_write_b32 v41, v32 offset:192
	v_add_u32_e32 v32, s0, v117
	s_lshl_b32 s0, s12, 8
	s_waitcnt lgkmcnt(0)
	s_barrier
	ds_read2st64_b32 v[32:33], v32 offset1:1
	s_add_i32 s0, s2, s0
	v_add_u32_e32 v34, s0, v117
	v_readlane_b32 s0, v254, 33
	s_or_b32 s13, s0, 3
	s_lshl_b32 s0, s13, 8
	s_add_i32 s0, s2, s0
	v_add_u32_e32 v40, s0, v117
	ds_read_b32 v35, v34
	ds_read_b32 v34, v40
	s_waitcnt lgkmcnt(0)
	s_lshr_b32 s30, s14, 6
	v_mov_b32_e32 v40, 0
	v_mov_b32_e32 v41, 0
	v_mov_b32_e32 v42, 0
	v_mov_b32_e32 v43, 0
	v_readlane_b32 s0, v32, 0
	v_readlane_b32 s1, v33, 0
	v_readlane_b32 s2, v35, 0
	v_readlane_b32 s3, v34, 0
	s_lshl_b64 s[26:27], -1, 1
	v_cmp_gt_f32_e64 s[4:5], s0, v32
	v_cmp_gt_f32_e64 s[6:7], s1, v33
	v_cmp_gt_f32_e64 s[8:9], s2, v35
	v_cmp_gt_f32_e64 s[16:17], s3, v34
	v_cmp_eq_f32_e64 s[18:19], s0, v32
	v_cmp_eq_f32_e64 s[20:21], s1, v33
	v_cmp_eq_f32_e64 s[22:23], s2, v35
	v_cmp_eq_f32_e64 s[24:25], s3, v34
	s_and_b64 s[18:19], s[18:19], s[26:27]
	s_or_b64 s[4:5], s[4:5], s[18:19]
	s_and_b64 s[20:21], s[20:21], s[26:27]
	s_or_b64 s[6:7], s[6:7], s[20:21]
	s_and_b64 s[22:23], s[22:23], s[26:27]
	s_or_b64 s[8:9], s[8:9], s[22:23]
	s_and_b64 s[24:25], s[24:25], s[26:27]
	s_or_b64 s[16:17], s[16:17], s[24:25]
	v_addc_co_u32_e64 v40, s[28:29], 0, v40, s[4:5]
	v_addc_co_u32_e64 v41, s[28:29], 0, v41, s[6:7]
	v_addc_co_u32_e64 v42, s[28:29], 0, v42, s[8:9]
	v_addc_co_u32_e64 v43, s[28:29], 0, v43, s[16:17]
	v_readlane_b32 s0, v32, 1
	v_readlane_b32 s1, v33, 1
	v_readlane_b32 s2, v35, 1
	v_readlane_b32 s3, v34, 1
	s_lshl_b64 s[26:27], -1, 2
	v_cmp_gt_f32_e64 s[4:5], s0, v32
	v_cmp_gt_f32_e64 s[6:7], s1, v33
	v_cmp_gt_f32_e64 s[8:9], s2, v35
	v_cmp_gt_f32_e64 s[16:17], s3, v34
	v_cmp_eq_f32_e64 s[18:19], s0, v32
	v_cmp_eq_f32_e64 s[20:21], s1, v33
	v_cmp_eq_f32_e64 s[22:23], s2, v35
	v_cmp_eq_f32_e64 s[24:25], s3, v34
	s_and_b64 s[18:19], s[18:19], s[26:27]
	s_or_b64 s[4:5], s[4:5], s[18:19]
	s_and_b64 s[20:21], s[20:21], s[26:27]
	s_or_b64 s[6:7], s[6:7], s[20:21]
	s_and_b64 s[22:23], s[22:23], s[26:27]
	s_or_b64 s[8:9], s[8:9], s[22:23]
	s_and_b64 s[24:25], s[24:25], s[26:27]
	s_or_b64 s[16:17], s[16:17], s[24:25]
	v_addc_co_u32_e64 v40, s[28:29], 0, v40, s[4:5]
	v_addc_co_u32_e64 v41, s[28:29], 0, v41, s[6:7]
	v_addc_co_u32_e64 v42, s[28:29], 0, v42, s[8:9]
	v_addc_co_u32_e64 v43, s[28:29], 0, v43, s[16:17]
	v_readlane_b32 s0, v32, 2
	v_readlane_b32 s1, v33, 2
	v_readlane_b32 s2, v35, 2
	v_readlane_b32 s3, v34, 2
	s_lshl_b64 s[26:27], -1, 3
	v_cmp_gt_f32_e64 s[4:5], s0, v32
	v_cmp_gt_f32_e64 s[6:7], s1, v33
	v_cmp_gt_f32_e64 s[8:9], s2, v35
	v_cmp_gt_f32_e64 s[16:17], s3, v34
	v_cmp_eq_f32_e64 s[18:19], s0, v32
	v_cmp_eq_f32_e64 s[20:21], s1, v33
	v_cmp_eq_f32_e64 s[22:23], s2, v35
	v_cmp_eq_f32_e64 s[24:25], s3, v34
	s_and_b64 s[18:19], s[18:19], s[26:27]
	s_or_b64 s[4:5], s[4:5], s[18:19]
	s_and_b64 s[20:21], s[20:21], s[26:27]
	s_or_b64 s[6:7], s[6:7], s[20:21]
	s_and_b64 s[22:23], s[22:23], s[26:27]
	s_or_b64 s[8:9], s[8:9], s[22:23]
	s_and_b64 s[24:25], s[24:25], s[26:27]
	s_or_b64 s[16:17], s[16:17], s[24:25]
	v_addc_co_u32_e64 v40, s[28:29], 0, v40, s[4:5]
	v_addc_co_u32_e64 v41, s[28:29], 0, v41, s[6:7]
	v_addc_co_u32_e64 v42, s[28:29], 0, v42, s[8:9]
	v_addc_co_u32_e64 v43, s[28:29], 0, v43, s[16:17]
	v_readlane_b32 s0, v32, 3
	v_readlane_b32 s1, v33, 3
	v_readlane_b32 s2, v35, 3
	v_readlane_b32 s3, v34, 3
	s_lshl_b64 s[26:27], -1, 4
	v_cmp_gt_f32_e64 s[4:5], s0, v32
	v_cmp_gt_f32_e64 s[6:7], s1, v33
	v_cmp_gt_f32_e64 s[8:9], s2, v35
	v_cmp_gt_f32_e64 s[16:17], s3, v34
	v_cmp_eq_f32_e64 s[18:19], s0, v32
	v_cmp_eq_f32_e64 s[20:21], s1, v33
	v_cmp_eq_f32_e64 s[22:23], s2, v35
	v_cmp_eq_f32_e64 s[24:25], s3, v34
	s_and_b64 s[18:19], s[18:19], s[26:27]
	s_or_b64 s[4:5], s[4:5], s[18:19]
	s_and_b64 s[20:21], s[20:21], s[26:27]
	s_or_b64 s[6:7], s[6:7], s[20:21]
	s_and_b64 s[22:23], s[22:23], s[26:27]
	s_or_b64 s[8:9], s[8:9], s[22:23]
	s_and_b64 s[24:25], s[24:25], s[26:27]
	s_or_b64 s[16:17], s[16:17], s[24:25]
	v_addc_co_u32_e64 v40, s[28:29], 0, v40, s[4:5]
	v_addc_co_u32_e64 v41, s[28:29], 0, v41, s[6:7]
	v_addc_co_u32_e64 v42, s[28:29], 0, v42, s[8:9]
	v_addc_co_u32_e64 v43, s[28:29], 0, v43, s[16:17]
	s_cmp_lt_u32 s30, 4
	s_cbranch_scc1 .Lnsa_rank_done
	v_readlane_b32 s0, v32, 4
	v_readlane_b32 s1, v33, 4
	v_readlane_b32 s2, v35, 4
	v_readlane_b32 s3, v34, 4
	s_lshl_b64 s[26:27], -1, 5
	v_cmp_gt_f32_e64 s[4:5], s0, v32
	v_cmp_gt_f32_e64 s[6:7], s1, v33
	v_cmp_gt_f32_e64 s[8:9], s2, v35
	v_cmp_gt_f32_e64 s[16:17], s3, v34
	v_cmp_eq_f32_e64 s[18:19], s0, v32
	v_cmp_eq_f32_e64 s[20:21], s1, v33
	v_cmp_eq_f32_e64 s[22:23], s2, v35
	v_cmp_eq_f32_e64 s[24:25], s3, v34
	s_and_b64 s[18:19], s[18:19], s[26:27]
	s_or_b64 s[4:5], s[4:5], s[18:19]
	s_and_b64 s[20:21], s[20:21], s[26:27]
	s_or_b64 s[6:7], s[6:7], s[20:21]
	s_and_b64 s[22:23], s[22:23], s[26:27]
	s_or_b64 s[8:9], s[8:9], s[22:23]
	s_and_b64 s[24:25], s[24:25], s[26:27]
	s_or_b64 s[16:17], s[16:17], s[24:25]
	v_addc_co_u32_e64 v40, s[28:29], 0, v40, s[4:5]
	v_addc_co_u32_e64 v41, s[28:29], 0, v41, s[6:7]
	v_addc_co_u32_e64 v42, s[28:29], 0, v42, s[8:9]
	v_addc_co_u32_e64 v43, s[28:29], 0, v43, s[16:17]
	v_readlane_b32 s0, v32, 5
	v_readlane_b32 s1, v33, 5
	v_readlane_b32 s2, v35, 5
	v_readlane_b32 s3, v34, 5
	s_lshl_b64 s[26:27], -1, 6
	v_cmp_gt_f32_e64 s[4:5], s0, v32
	v_cmp_gt_f32_e64 s[6:7], s1, v33
	v_cmp_gt_f32_e64 s[8:9], s2, v35
	v_cmp_gt_f32_e64 s[16:17], s3, v34
	v_cmp_eq_f32_e64 s[18:19], s0, v32
	v_cmp_eq_f32_e64 s[20:21], s1, v33
	v_cmp_eq_f32_e64 s[22:23], s2, v35
	v_cmp_eq_f32_e64 s[24:25], s3, v34
	s_and_b64 s[18:19], s[18:19], s[26:27]
	s_or_b64 s[4:5], s[4:5], s[18:19]
	s_and_b64 s[20:21], s[20:21], s[26:27]
	s_or_b64 s[6:7], s[6:7], s[20:21]
	s_and_b64 s[22:23], s[22:23], s[26:27]
	s_or_b64 s[8:9], s[8:9], s[22:23]
	s_and_b64 s[24:25], s[24:25], s[26:27]
	s_or_b64 s[16:17], s[16:17], s[24:25]
	v_addc_co_u32_e64 v40, s[28:29], 0, v40, s[4:5]
	v_addc_co_u32_e64 v41, s[28:29], 0, v41, s[6:7]
	v_addc_co_u32_e64 v42, s[28:29], 0, v42, s[8:9]
	v_addc_co_u32_e64 v43, s[28:29], 0, v43, s[16:17]
	v_readlane_b32 s0, v32, 6
	v_readlane_b32 s1, v33, 6
	v_readlane_b32 s2, v35, 6
	v_readlane_b32 s3, v34, 6
	s_lshl_b64 s[26:27], -1, 7
	v_cmp_gt_f32_e64 s[4:5], s0, v32
	v_cmp_gt_f32_e64 s[6:7], s1, v33
	v_cmp_gt_f32_e64 s[8:9], s2, v35
	v_cmp_gt_f32_e64 s[16:17], s3, v34
	v_cmp_eq_f32_e64 s[18:19], s0, v32
	v_cmp_eq_f32_e64 s[20:21], s1, v33
	v_cmp_eq_f32_e64 s[22:23], s2, v35
	v_cmp_eq_f32_e64 s[24:25], s3, v34
	s_and_b64 s[18:19], s[18:19], s[26:27]
	s_or_b64 s[4:5], s[4:5], s[18:19]
	s_and_b64 s[20:21], s[20:21], s[26:27]
	s_or_b64 s[6:7], s[6:7], s[20:21]
	s_and_b64 s[22:23], s[22:23], s[26:27]
	s_or_b64 s[8:9], s[8:9], s[22:23]
	s_and_b64 s[24:25], s[24:25], s[26:27]
	s_or_b64 s[16:17], s[16:17], s[24:25]
	v_addc_co_u32_e64 v40, s[28:29], 0, v40, s[4:5]
	v_addc_co_u32_e64 v41, s[28:29], 0, v41, s[6:7]
	v_addc_co_u32_e64 v42, s[28:29], 0, v42, s[8:9]
	v_addc_co_u32_e64 v43, s[28:29], 0, v43, s[16:17]
	v_readlane_b32 s0, v32, 7
	v_readlane_b32 s1, v33, 7
	v_readlane_b32 s2, v35, 7
	v_readlane_b32 s3, v34, 7
	s_lshl_b64 s[26:27], -1, 8
	v_cmp_gt_f32_e64 s[4:5], s0, v32
	v_cmp_gt_f32_e64 s[6:7], s1, v33
	v_cmp_gt_f32_e64 s[8:9], s2, v35
	v_cmp_gt_f32_e64 s[16:17], s3, v34
	v_cmp_eq_f32_e64 s[18:19], s0, v32
	v_cmp_eq_f32_e64 s[20:21], s1, v33
	v_cmp_eq_f32_e64 s[22:23], s2, v35
	v_cmp_eq_f32_e64 s[24:25], s3, v34
	s_and_b64 s[18:19], s[18:19], s[26:27]
	s_or_b64 s[4:5], s[4:5], s[18:19]
	s_and_b64 s[20:21], s[20:21], s[26:27]
	s_or_b64 s[6:7], s[6:7], s[20:21]
	s_and_b64 s[22:23], s[22:23], s[26:27]
	s_or_b64 s[8:9], s[8:9], s[22:23]
	s_and_b64 s[24:25], s[24:25], s[26:27]
	s_or_b64 s[16:17], s[16:17], s[24:25]
	v_addc_co_u32_e64 v40, s[28:29], 0, v40, s[4:5]
	v_addc_co_u32_e64 v41, s[28:29], 0, v41, s[6:7]
	v_addc_co_u32_e64 v42, s[28:29], 0, v42, s[8:9]
	v_addc_co_u32_e64 v43, s[28:29], 0, v43, s[16:17]
	s_cmp_lt_u32 s30, 8
	s_cbranch_scc1 .Lnsa_rank_done
	v_readlane_b32 s0, v32, 8
	v_readlane_b32 s1, v33, 8
	v_readlane_b32 s2, v35, 8
	v_readlane_b32 s3, v34, 8
	s_lshl_b64 s[26:27], -1, 9
	v_cmp_gt_f32_e64 s[4:5], s0, v32
	v_cmp_gt_f32_e64 s[6:7], s1, v33
	v_cmp_gt_f32_e64 s[8:9], s2, v35
	v_cmp_gt_f32_e64 s[16:17], s3, v34
	v_cmp_eq_f32_e64 s[18:19], s0, v32
	v_cmp_eq_f32_e64 s[20:21], s1, v33
	v_cmp_eq_f32_e64 s[22:23], s2, v35
	v_cmp_eq_f32_e64 s[24:25], s3, v34
	s_and_b64 s[18:19], s[18:19], s[26:27]
	s_or_b64 s[4:5], s[4:5], s[18:19]
	s_and_b64 s[20:21], s[20:21], s[26:27]
	s_or_b64 s[6:7], s[6:7], s[20:21]
	s_and_b64 s[22:23], s[22:23], s[26:27]
	s_or_b64 s[8:9], s[8:9], s[22:23]
	s_and_b64 s[24:25], s[24:25], s[26:27]
	s_or_b64 s[16:17], s[16:17], s[24:25]
	v_addc_co_u32_e64 v40, s[28:29], 0, v40, s[4:5]
	v_addc_co_u32_e64 v41, s[28:29], 0, v41, s[6:7]
	v_addc_co_u32_e64 v42, s[28:29], 0, v42, s[8:9]
	v_addc_co_u32_e64 v43, s[28:29], 0, v43, s[16:17]
	v_readlane_b32 s0, v32, 9
	v_readlane_b32 s1, v33, 9
	v_readlane_b32 s2, v35, 9
	v_readlane_b32 s3, v34, 9
	s_lshl_b64 s[26:27], -1, 10
	v_cmp_gt_f32_e64 s[4:5], s0, v32
	v_cmp_gt_f32_e64 s[6:7], s1, v33
	v_cmp_gt_f32_e64 s[8:9], s2, v35
	v_cmp_gt_f32_e64 s[16:17], s3, v34
	v_cmp_eq_f32_e64 s[18:19], s0, v32
	v_cmp_eq_f32_e64 s[20:21], s1, v33
	v_cmp_eq_f32_e64 s[22:23], s2, v35
	v_cmp_eq_f32_e64 s[24:25], s3, v34
	s_and_b64 s[18:19], s[18:19], s[26:27]
	s_or_b64 s[4:5], s[4:5], s[18:19]
	s_and_b64 s[20:21], s[20:21], s[26:27]
	s_or_b64 s[6:7], s[6:7], s[20:21]
	s_and_b64 s[22:23], s[22:23], s[26:27]
	s_or_b64 s[8:9], s[8:9], s[22:23]
	s_and_b64 s[24:25], s[24:25], s[26:27]
	s_or_b64 s[16:17], s[16:17], s[24:25]
	v_addc_co_u32_e64 v40, s[28:29], 0, v40, s[4:5]
	v_addc_co_u32_e64 v41, s[28:29], 0, v41, s[6:7]
	v_addc_co_u32_e64 v42, s[28:29], 0, v42, s[8:9]
	v_addc_co_u32_e64 v43, s[28:29], 0, v43, s[16:17]
	v_readlane_b32 s0, v32, 10
	v_readlane_b32 s1, v33, 10
	v_readlane_b32 s2, v35, 10
	v_readlane_b32 s3, v34, 10
	s_lshl_b64 s[26:27], -1, 11
	v_cmp_gt_f32_e64 s[4:5], s0, v32
	v_cmp_gt_f32_e64 s[6:7], s1, v33
	v_cmp_gt_f32_e64 s[8:9], s2, v35
	v_cmp_gt_f32_e64 s[16:17], s3, v34
	v_cmp_eq_f32_e64 s[18:19], s0, v32
	v_cmp_eq_f32_e64 s[20:21], s1, v33
	v_cmp_eq_f32_e64 s[22:23], s2, v35
	v_cmp_eq_f32_e64 s[24:25], s3, v34
	s_and_b64 s[18:19], s[18:19], s[26:27]
	s_or_b64 s[4:5], s[4:5], s[18:19]
	s_and_b64 s[20:21], s[20:21], s[26:27]
	s_or_b64 s[6:7], s[6:7], s[20:21]
	s_and_b64 s[22:23], s[22:23], s[26:27]
	s_or_b64 s[8:9], s[8:9], s[22:23]
	s_and_b64 s[24:25], s[24:25], s[26:27]
	s_or_b64 s[16:17], s[16:17], s[24:25]
	v_addc_co_u32_e64 v40, s[28:29], 0, v40, s[4:5]
	v_addc_co_u32_e64 v41, s[28:29], 0, v41, s[6:7]
	v_addc_co_u32_e64 v42, s[28:29], 0, v42, s[8:9]
	v_addc_co_u32_e64 v43, s[28:29], 0, v43, s[16:17]
	v_readlane_b32 s0, v32, 11
	v_readlane_b32 s1, v33, 11
	v_readlane_b32 s2, v35, 11
	v_readlane_b32 s3, v34, 11
	s_lshl_b64 s[26:27], -1, 12
	v_cmp_gt_f32_e64 s[4:5], s0, v32
	v_cmp_gt_f32_e64 s[6:7], s1, v33
	v_cmp_gt_f32_e64 s[8:9], s2, v35
	v_cmp_gt_f32_e64 s[16:17], s3, v34
	v_cmp_eq_f32_e64 s[18:19], s0, v32
	v_cmp_eq_f32_e64 s[20:21], s1, v33
	v_cmp_eq_f32_e64 s[22:23], s2, v35
	v_cmp_eq_f32_e64 s[24:25], s3, v34
	s_and_b64 s[18:19], s[18:19], s[26:27]
	s_or_b64 s[4:5], s[4:5], s[18:19]
	s_and_b64 s[20:21], s[20:21], s[26:27]
	s_or_b64 s[6:7], s[6:7], s[20:21]
	s_and_b64 s[22:23], s[22:23], s[26:27]
	s_or_b64 s[8:9], s[8:9], s[22:23]
	s_and_b64 s[24:25], s[24:25], s[26:27]
	s_or_b64 s[16:17], s[16:17], s[24:25]
	v_addc_co_u32_e64 v40, s[28:29], 0, v40, s[4:5]
	v_addc_co_u32_e64 v41, s[28:29], 0, v41, s[6:7]
	v_addc_co_u32_e64 v42, s[28:29], 0, v42, s[8:9]
	v_addc_co_u32_e64 v43, s[28:29], 0, v43, s[16:17]
	s_cmp_lt_u32 s30, 12
	s_cbranch_scc1 .Lnsa_rank_done
	v_readlane_b32 s0, v32, 12
	v_readlane_b32 s1, v33, 12
	v_readlane_b32 s2, v35, 12
	v_readlane_b32 s3, v34, 12
	s_lshl_b64 s[26:27], -1, 13
	v_cmp_gt_f32_e64 s[4:5], s0, v32
	v_cmp_gt_f32_e64 s[6:7], s1, v33
	v_cmp_gt_f32_e64 s[8:9], s2, v35
	v_cmp_gt_f32_e64 s[16:17], s3, v34
	v_cmp_eq_f32_e64 s[18:19], s0, v32
	v_cmp_eq_f32_e64 s[20:21], s1, v33
	v_cmp_eq_f32_e64 s[22:23], s2, v35
	v_cmp_eq_f32_e64 s[24:25], s3, v34
	s_and_b64 s[18:19], s[18:19], s[26:27]
	s_or_b64 s[4:5], s[4:5], s[18:19]
	s_and_b64 s[20:21], s[20:21], s[26:27]
	s_or_b64 s[6:7], s[6:7], s[20:21]
	s_and_b64 s[22:23], s[22:23], s[26:27]
	s_or_b64 s[8:9], s[8:9], s[22:23]
	s_and_b64 s[24:25], s[24:25], s[26:27]
	s_or_b64 s[16:17], s[16:17], s[24:25]
	v_addc_co_u32_e64 v40, s[28:29], 0, v40, s[4:5]
	v_addc_co_u32_e64 v41, s[28:29], 0, v41, s[6:7]
	v_addc_co_u32_e64 v42, s[28:29], 0, v42, s[8:9]
	v_addc_co_u32_e64 v43, s[28:29], 0, v43, s[16:17]
	v_readlane_b32 s0, v32, 13
	v_readlane_b32 s1, v33, 13
	v_readlane_b32 s2, v35, 13
	v_readlane_b32 s3, v34, 13
	s_lshl_b64 s[26:27], -1, 14
	v_cmp_gt_f32_e64 s[4:5], s0, v32
	v_cmp_gt_f32_e64 s[6:7], s1, v33
	v_cmp_gt_f32_e64 s[8:9], s2, v35
	v_cmp_gt_f32_e64 s[16:17], s3, v34
	v_cmp_eq_f32_e64 s[18:19], s0, v32
	v_cmp_eq_f32_e64 s[20:21], s1, v33
	v_cmp_eq_f32_e64 s[22:23], s2, v35
	v_cmp_eq_f32_e64 s[24:25], s3, v34
	s_and_b64 s[18:19], s[18:19], s[26:27]
	s_or_b64 s[4:5], s[4:5], s[18:19]
	s_and_b64 s[20:21], s[20:21], s[26:27]
	s_or_b64 s[6:7], s[6:7], s[20:21]
	s_and_b64 s[22:23], s[22:23], s[26:27]
	s_or_b64 s[8:9], s[8:9], s[22:23]
	s_and_b64 s[24:25], s[24:25], s[26:27]
	s_or_b64 s[16:17], s[16:17], s[24:25]
	v_addc_co_u32_e64 v40, s[28:29], 0, v40, s[4:5]
	v_addc_co_u32_e64 v41, s[28:29], 0, v41, s[6:7]
	v_addc_co_u32_e64 v42, s[28:29], 0, v42, s[8:9]
	v_addc_co_u32_e64 v43, s[28:29], 0, v43, s[16:17]
	v_readlane_b32 s0, v32, 14
	v_readlane_b32 s1, v33, 14
	v_readlane_b32 s2, v35, 14
	v_readlane_b32 s3, v34, 14
	s_lshl_b64 s[26:27], -1, 15
	v_cmp_gt_f32_e64 s[4:5], s0, v32
	v_cmp_gt_f32_e64 s[6:7], s1, v33
	v_cmp_gt_f32_e64 s[8:9], s2, v35
	v_cmp_gt_f32_e64 s[16:17], s3, v34
	v_cmp_eq_f32_e64 s[18:19], s0, v32
	v_cmp_eq_f32_e64 s[20:21], s1, v33
	v_cmp_eq_f32_e64 s[22:23], s2, v35
	v_cmp_eq_f32_e64 s[24:25], s3, v34
	s_and_b64 s[18:19], s[18:19], s[26:27]
	s_or_b64 s[4:5], s[4:5], s[18:19]
	s_and_b64 s[20:21], s[20:21], s[26:27]
	s_or_b64 s[6:7], s[6:7], s[20:21]
	s_and_b64 s[22:23], s[22:23], s[26:27]
	s_or_b64 s[8:9], s[8:9], s[22:23]
	s_and_b64 s[24:25], s[24:25], s[26:27]
	s_or_b64 s[16:17], s[16:17], s[24:25]
	v_addc_co_u32_e64 v40, s[28:29], 0, v40, s[4:5]
	v_addc_co_u32_e64 v41, s[28:29], 0, v41, s[6:7]
	v_addc_co_u32_e64 v42, s[28:29], 0, v42, s[8:9]
	v_addc_co_u32_e64 v43, s[28:29], 0, v43, s[16:17]
	v_readlane_b32 s0, v32, 15
	v_readlane_b32 s1, v33, 15
	v_readlane_b32 s2, v35, 15
	v_readlane_b32 s3, v34, 15
	s_lshl_b64 s[26:27], -1, 16
	v_cmp_gt_f32_e64 s[4:5], s0, v32
	v_cmp_gt_f32_e64 s[6:7], s1, v33
	v_cmp_gt_f32_e64 s[8:9], s2, v35
	v_cmp_gt_f32_e64 s[16:17], s3, v34
	v_cmp_eq_f32_e64 s[18:19], s0, v32
	v_cmp_eq_f32_e64 s[20:21], s1, v33
	v_cmp_eq_f32_e64 s[22:23], s2, v35
	v_cmp_eq_f32_e64 s[24:25], s3, v34
	s_and_b64 s[18:19], s[18:19], s[26:27]
	s_or_b64 s[4:5], s[4:5], s[18:19]
	s_and_b64 s[20:21], s[20:21], s[26:27]
	s_or_b64 s[6:7], s[6:7], s[20:21]
	s_and_b64 s[22:23], s[22:23], s[26:27]
	s_or_b64 s[8:9], s[8:9], s[22:23]
	s_and_b64 s[24:25], s[24:25], s[26:27]
	s_or_b64 s[16:17], s[16:17], s[24:25]
	v_addc_co_u32_e64 v40, s[28:29], 0, v40, s[4:5]
	v_addc_co_u32_e64 v41, s[28:29], 0, v41, s[6:7]
	v_addc_co_u32_e64 v42, s[28:29], 0, v42, s[8:9]
	v_addc_co_u32_e64 v43, s[28:29], 0, v43, s[16:17]
	s_cmp_lt_u32 s30, 16
	s_cbranch_scc1 .Lnsa_rank_done
	v_readlane_b32 s0, v32, 16
	v_readlane_b32 s1, v33, 16
	v_readlane_b32 s2, v35, 16
	v_readlane_b32 s3, v34, 16
	s_lshl_b64 s[26:27], -1, 17
	v_cmp_gt_f32_e64 s[4:5], s0, v32
	v_cmp_gt_f32_e64 s[6:7], s1, v33
	v_cmp_gt_f32_e64 s[8:9], s2, v35
	v_cmp_gt_f32_e64 s[16:17], s3, v34
	v_cmp_eq_f32_e64 s[18:19], s0, v32
	v_cmp_eq_f32_e64 s[20:21], s1, v33
	v_cmp_eq_f32_e64 s[22:23], s2, v35
	v_cmp_eq_f32_e64 s[24:25], s3, v34
	s_and_b64 s[18:19], s[18:19], s[26:27]
	s_or_b64 s[4:5], s[4:5], s[18:19]
	s_and_b64 s[20:21], s[20:21], s[26:27]
	s_or_b64 s[6:7], s[6:7], s[20:21]
	s_and_b64 s[22:23], s[22:23], s[26:27]
	s_or_b64 s[8:9], s[8:9], s[22:23]
	s_and_b64 s[24:25], s[24:25], s[26:27]
	s_or_b64 s[16:17], s[16:17], s[24:25]
	v_addc_co_u32_e64 v40, s[28:29], 0, v40, s[4:5]
	v_addc_co_u32_e64 v41, s[28:29], 0, v41, s[6:7]
	v_addc_co_u32_e64 v42, s[28:29], 0, v42, s[8:9]
	v_addc_co_u32_e64 v43, s[28:29], 0, v43, s[16:17]
	v_readlane_b32 s0, v32, 17
	v_readlane_b32 s1, v33, 17
	v_readlane_b32 s2, v35, 17
	v_readlane_b32 s3, v34, 17
	s_lshl_b64 s[26:27], -1, 18
	v_cmp_gt_f32_e64 s[4:5], s0, v32
	v_cmp_gt_f32_e64 s[6:7], s1, v33
	v_cmp_gt_f32_e64 s[8:9], s2, v35
	v_cmp_gt_f32_e64 s[16:17], s3, v34
	v_cmp_eq_f32_e64 s[18:19], s0, v32
	v_cmp_eq_f32_e64 s[20:21], s1, v33
	v_cmp_eq_f32_e64 s[22:23], s2, v35
	v_cmp_eq_f32_e64 s[24:25], s3, v34
	s_and_b64 s[18:19], s[18:19], s[26:27]
	s_or_b64 s[4:5], s[4:5], s[18:19]
	s_and_b64 s[20:21], s[20:21], s[26:27]
	s_or_b64 s[6:7], s[6:7], s[20:21]
	s_and_b64 s[22:23], s[22:23], s[26:27]
	s_or_b64 s[8:9], s[8:9], s[22:23]
	s_and_b64 s[24:25], s[24:25], s[26:27]
	s_or_b64 s[16:17], s[16:17], s[24:25]
	v_addc_co_u32_e64 v40, s[28:29], 0, v40, s[4:5]
	v_addc_co_u32_e64 v41, s[28:29], 0, v41, s[6:7]
	v_addc_co_u32_e64 v42, s[28:29], 0, v42, s[8:9]
	v_addc_co_u32_e64 v43, s[28:29], 0, v43, s[16:17]
	v_readlane_b32 s0, v32, 18
	v_readlane_b32 s1, v33, 18
	v_readlane_b32 s2, v35, 18
	v_readlane_b32 s3, v34, 18
	s_lshl_b64 s[26:27], -1, 19
	v_cmp_gt_f32_e64 s[4:5], s0, v32
	v_cmp_gt_f32_e64 s[6:7], s1, v33
	v_cmp_gt_f32_e64 s[8:9], s2, v35
	v_cmp_gt_f32_e64 s[16:17], s3, v34
	v_cmp_eq_f32_e64 s[18:19], s0, v32
	v_cmp_eq_f32_e64 s[20:21], s1, v33
	v_cmp_eq_f32_e64 s[22:23], s2, v35
	v_cmp_eq_f32_e64 s[24:25], s3, v34
	s_and_b64 s[18:19], s[18:19], s[26:27]
	s_or_b64 s[4:5], s[4:5], s[18:19]
	s_and_b64 s[20:21], s[20:21], s[26:27]
	s_or_b64 s[6:7], s[6:7], s[20:21]
	s_and_b64 s[22:23], s[22:23], s[26:27]
	s_or_b64 s[8:9], s[8:9], s[22:23]
	s_and_b64 s[24:25], s[24:25], s[26:27]
	s_or_b64 s[16:17], s[16:17], s[24:25]
	v_addc_co_u32_e64 v40, s[28:29], 0, v40, s[4:5]
	v_addc_co_u32_e64 v41, s[28:29], 0, v41, s[6:7]
	v_addc_co_u32_e64 v42, s[28:29], 0, v42, s[8:9]
	v_addc_co_u32_e64 v43, s[28:29], 0, v43, s[16:17]
	v_readlane_b32 s0, v32, 19
	v_readlane_b32 s1, v33, 19
	v_readlane_b32 s2, v35, 19
	v_readlane_b32 s3, v34, 19
	s_lshl_b64 s[26:27], -1, 20
	v_cmp_gt_f32_e64 s[4:5], s0, v32
	v_cmp_gt_f32_e64 s[6:7], s1, v33
	v_cmp_gt_f32_e64 s[8:9], s2, v35
	v_cmp_gt_f32_e64 s[16:17], s3, v34
	v_cmp_eq_f32_e64 s[18:19], s0, v32
	v_cmp_eq_f32_e64 s[20:21], s1, v33
	v_cmp_eq_f32_e64 s[22:23], s2, v35
	v_cmp_eq_f32_e64 s[24:25], s3, v34
	s_and_b64 s[18:19], s[18:19], s[26:27]
	s_or_b64 s[4:5], s[4:5], s[18:19]
	s_and_b64 s[20:21], s[20:21], s[26:27]
	s_or_b64 s[6:7], s[6:7], s[20:21]
	s_and_b64 s[22:23], s[22:23], s[26:27]
	s_or_b64 s[8:9], s[8:9], s[22:23]
	s_and_b64 s[24:25], s[24:25], s[26:27]
	s_or_b64 s[16:17], s[16:17], s[24:25]
	v_addc_co_u32_e64 v40, s[28:29], 0, v40, s[4:5]
	v_addc_co_u32_e64 v41, s[28:29], 0, v41, s[6:7]
	v_addc_co_u32_e64 v42, s[28:29], 0, v42, s[8:9]
	v_addc_co_u32_e64 v43, s[28:29], 0, v43, s[16:17]
	s_cmp_lt_u32 s30, 20
	s_cbranch_scc1 .Lnsa_rank_done
	v_readlane_b32 s0, v32, 20
	v_readlane_b32 s1, v33, 20
	v_readlane_b32 s2, v35, 20
	v_readlane_b32 s3, v34, 20
	s_lshl_b64 s[26:27], -1, 21
	v_cmp_gt_f32_e64 s[4:5], s0, v32
	v_cmp_gt_f32_e64 s[6:7], s1, v33
	v_cmp_gt_f32_e64 s[8:9], s2, v35
	v_cmp_gt_f32_e64 s[16:17], s3, v34
	v_cmp_eq_f32_e64 s[18:19], s0, v32
	v_cmp_eq_f32_e64 s[20:21], s1, v33
	v_cmp_eq_f32_e64 s[22:23], s2, v35
	v_cmp_eq_f32_e64 s[24:25], s3, v34
	s_and_b64 s[18:19], s[18:19], s[26:27]
	s_or_b64 s[4:5], s[4:5], s[18:19]
	s_and_b64 s[20:21], s[20:21], s[26:27]
	s_or_b64 s[6:7], s[6:7], s[20:21]
	s_and_b64 s[22:23], s[22:23], s[26:27]
	s_or_b64 s[8:9], s[8:9], s[22:23]
	s_and_b64 s[24:25], s[24:25], s[26:27]
	s_or_b64 s[16:17], s[16:17], s[24:25]
	v_addc_co_u32_e64 v40, s[28:29], 0, v40, s[4:5]
	v_addc_co_u32_e64 v41, s[28:29], 0, v41, s[6:7]
	v_addc_co_u32_e64 v42, s[28:29], 0, v42, s[8:9]
	v_addc_co_u32_e64 v43, s[28:29], 0, v43, s[16:17]
	v_readlane_b32 s0, v32, 21
	v_readlane_b32 s1, v33, 21
	v_readlane_b32 s2, v35, 21
	v_readlane_b32 s3, v34, 21
	s_lshl_b64 s[26:27], -1, 22
	v_cmp_gt_f32_e64 s[4:5], s0, v32
	v_cmp_gt_f32_e64 s[6:7], s1, v33
	v_cmp_gt_f32_e64 s[8:9], s2, v35
	v_cmp_gt_f32_e64 s[16:17], s3, v34
	v_cmp_eq_f32_e64 s[18:19], s0, v32
	v_cmp_eq_f32_e64 s[20:21], s1, v33
	v_cmp_eq_f32_e64 s[22:23], s2, v35
	v_cmp_eq_f32_e64 s[24:25], s3, v34
	s_and_b64 s[18:19], s[18:19], s[26:27]
	s_or_b64 s[4:5], s[4:5], s[18:19]
	s_and_b64 s[20:21], s[20:21], s[26:27]
	s_or_b64 s[6:7], s[6:7], s[20:21]
	s_and_b64 s[22:23], s[22:23], s[26:27]
	s_or_b64 s[8:9], s[8:9], s[22:23]
	s_and_b64 s[24:25], s[24:25], s[26:27]
	s_or_b64 s[16:17], s[16:17], s[24:25]
	v_addc_co_u32_e64 v40, s[28:29], 0, v40, s[4:5]
	v_addc_co_u32_e64 v41, s[28:29], 0, v41, s[6:7]
	v_addc_co_u32_e64 v42, s[28:29], 0, v42, s[8:9]
	v_addc_co_u32_e64 v43, s[28:29], 0, v43, s[16:17]
	v_readlane_b32 s0, v32, 22
	v_readlane_b32 s1, v33, 22
	v_readlane_b32 s2, v35, 22
	v_readlane_b32 s3, v34, 22
	s_lshl_b64 s[26:27], -1, 23
	v_cmp_gt_f32_e64 s[4:5], s0, v32
	v_cmp_gt_f32_e64 s[6:7], s1, v33
	v_cmp_gt_f32_e64 s[8:9], s2, v35
	v_cmp_gt_f32_e64 s[16:17], s3, v34
	v_cmp_eq_f32_e64 s[18:19], s0, v32
	v_cmp_eq_f32_e64 s[20:21], s1, v33
	v_cmp_eq_f32_e64 s[22:23], s2, v35
	v_cmp_eq_f32_e64 s[24:25], s3, v34
	s_and_b64 s[18:19], s[18:19], s[26:27]
	s_or_b64 s[4:5], s[4:5], s[18:19]
	s_and_b64 s[20:21], s[20:21], s[26:27]
	s_or_b64 s[6:7], s[6:7], s[20:21]
	s_and_b64 s[22:23], s[22:23], s[26:27]
	s_or_b64 s[8:9], s[8:9], s[22:23]
	s_and_b64 s[24:25], s[24:25], s[26:27]
	s_or_b64 s[16:17], s[16:17], s[24:25]
	v_addc_co_u32_e64 v40, s[28:29], 0, v40, s[4:5]
	v_addc_co_u32_e64 v41, s[28:29], 0, v41, s[6:7]
	v_addc_co_u32_e64 v42, s[28:29], 0, v42, s[8:9]
	v_addc_co_u32_e64 v43, s[28:29], 0, v43, s[16:17]
	v_readlane_b32 s0, v32, 23
	v_readlane_b32 s1, v33, 23
	v_readlane_b32 s2, v35, 23
	v_readlane_b32 s3, v34, 23
	s_lshl_b64 s[26:27], -1, 24
	v_cmp_gt_f32_e64 s[4:5], s0, v32
	v_cmp_gt_f32_e64 s[6:7], s1, v33
	v_cmp_gt_f32_e64 s[8:9], s2, v35
	v_cmp_gt_f32_e64 s[16:17], s3, v34
	v_cmp_eq_f32_e64 s[18:19], s0, v32
	v_cmp_eq_f32_e64 s[20:21], s1, v33
	v_cmp_eq_f32_e64 s[22:23], s2, v35
	v_cmp_eq_f32_e64 s[24:25], s3, v34
	s_and_b64 s[18:19], s[18:19], s[26:27]
	s_or_b64 s[4:5], s[4:5], s[18:19]
	s_and_b64 s[20:21], s[20:21], s[26:27]
	s_or_b64 s[6:7], s[6:7], s[20:21]
	s_and_b64 s[22:23], s[22:23], s[26:27]
	s_or_b64 s[8:9], s[8:9], s[22:23]
	s_and_b64 s[24:25], s[24:25], s[26:27]
	s_or_b64 s[16:17], s[16:17], s[24:25]
	v_addc_co_u32_e64 v40, s[28:29], 0, v40, s[4:5]
	v_addc_co_u32_e64 v41, s[28:29], 0, v41, s[6:7]
	v_addc_co_u32_e64 v42, s[28:29], 0, v42, s[8:9]
	v_addc_co_u32_e64 v43, s[28:29], 0, v43, s[16:17]
	s_cmp_lt_u32 s30, 24
	s_cbranch_scc1 .Lnsa_rank_done
	v_readlane_b32 s0, v32, 24
	v_readlane_b32 s1, v33, 24
	v_readlane_b32 s2, v35, 24
	v_readlane_b32 s3, v34, 24
	s_lshl_b64 s[26:27], -1, 25
	v_cmp_gt_f32_e64 s[4:5], s0, v32
	v_cmp_gt_f32_e64 s[6:7], s1, v33
	v_cmp_gt_f32_e64 s[8:9], s2, v35
	v_cmp_gt_f32_e64 s[16:17], s3, v34
	v_cmp_eq_f32_e64 s[18:19], s0, v32
	v_cmp_eq_f32_e64 s[20:21], s1, v33
	v_cmp_eq_f32_e64 s[22:23], s2, v35
	v_cmp_eq_f32_e64 s[24:25], s3, v34
	s_and_b64 s[18:19], s[18:19], s[26:27]
	s_or_b64 s[4:5], s[4:5], s[18:19]
	s_and_b64 s[20:21], s[20:21], s[26:27]
	s_or_b64 s[6:7], s[6:7], s[20:21]
	s_and_b64 s[22:23], s[22:23], s[26:27]
	s_or_b64 s[8:9], s[8:9], s[22:23]
	s_and_b64 s[24:25], s[24:25], s[26:27]
	s_or_b64 s[16:17], s[16:17], s[24:25]
	v_addc_co_u32_e64 v40, s[28:29], 0, v40, s[4:5]
	v_addc_co_u32_e64 v41, s[28:29], 0, v41, s[6:7]
	v_addc_co_u32_e64 v42, s[28:29], 0, v42, s[8:9]
	v_addc_co_u32_e64 v43, s[28:29], 0, v43, s[16:17]
	v_readlane_b32 s0, v32, 25
	v_readlane_b32 s1, v33, 25
	v_readlane_b32 s2, v35, 25
	v_readlane_b32 s3, v34, 25
	s_lshl_b64 s[26:27], -1, 26
	v_cmp_gt_f32_e64 s[4:5], s0, v32
	v_cmp_gt_f32_e64 s[6:7], s1, v33
	v_cmp_gt_f32_e64 s[8:9], s2, v35
	v_cmp_gt_f32_e64 s[16:17], s3, v34
	v_cmp_eq_f32_e64 s[18:19], s0, v32
	v_cmp_eq_f32_e64 s[20:21], s1, v33
	v_cmp_eq_f32_e64 s[22:23], s2, v35
	v_cmp_eq_f32_e64 s[24:25], s3, v34
	s_and_b64 s[18:19], s[18:19], s[26:27]
	s_or_b64 s[4:5], s[4:5], s[18:19]
	s_and_b64 s[20:21], s[20:21], s[26:27]
	s_or_b64 s[6:7], s[6:7], s[20:21]
	s_and_b64 s[22:23], s[22:23], s[26:27]
	s_or_b64 s[8:9], s[8:9], s[22:23]
	s_and_b64 s[24:25], s[24:25], s[26:27]
	s_or_b64 s[16:17], s[16:17], s[24:25]
	v_addc_co_u32_e64 v40, s[28:29], 0, v40, s[4:5]
	v_addc_co_u32_e64 v41, s[28:29], 0, v41, s[6:7]
	v_addc_co_u32_e64 v42, s[28:29], 0, v42, s[8:9]
	v_addc_co_u32_e64 v43, s[28:29], 0, v43, s[16:17]
	v_readlane_b32 s0, v32, 26
	v_readlane_b32 s1, v33, 26
	v_readlane_b32 s2, v35, 26
	v_readlane_b32 s3, v34, 26
	s_lshl_b64 s[26:27], -1, 27
	v_cmp_gt_f32_e64 s[4:5], s0, v32
	v_cmp_gt_f32_e64 s[6:7], s1, v33
	v_cmp_gt_f32_e64 s[8:9], s2, v35
	v_cmp_gt_f32_e64 s[16:17], s3, v34
	v_cmp_eq_f32_e64 s[18:19], s0, v32
	v_cmp_eq_f32_e64 s[20:21], s1, v33
	v_cmp_eq_f32_e64 s[22:23], s2, v35
	v_cmp_eq_f32_e64 s[24:25], s3, v34
	s_and_b64 s[18:19], s[18:19], s[26:27]
	s_or_b64 s[4:5], s[4:5], s[18:19]
	s_and_b64 s[20:21], s[20:21], s[26:27]
	s_or_b64 s[6:7], s[6:7], s[20:21]
	s_and_b64 s[22:23], s[22:23], s[26:27]
	s_or_b64 s[8:9], s[8:9], s[22:23]
	s_and_b64 s[24:25], s[24:25], s[26:27]
	s_or_b64 s[16:17], s[16:17], s[24:25]
	v_addc_co_u32_e64 v40, s[28:29], 0, v40, s[4:5]
	v_addc_co_u32_e64 v41, s[28:29], 0, v41, s[6:7]
	v_addc_co_u32_e64 v42, s[28:29], 0, v42, s[8:9]
	v_addc_co_u32_e64 v43, s[28:29], 0, v43, s[16:17]
	v_readlane_b32 s0, v32, 27
	v_readlane_b32 s1, v33, 27
	v_readlane_b32 s2, v35, 27
	v_readlane_b32 s3, v34, 27
	s_lshl_b64 s[26:27], -1, 28
	v_cmp_gt_f32_e64 s[4:5], s0, v32
	v_cmp_gt_f32_e64 s[6:7], s1, v33
	v_cmp_gt_f32_e64 s[8:9], s2, v35
	v_cmp_gt_f32_e64 s[16:17], s3, v34
	v_cmp_eq_f32_e64 s[18:19], s0, v32
	v_cmp_eq_f32_e64 s[20:21], s1, v33
	v_cmp_eq_f32_e64 s[22:23], s2, v35
	v_cmp_eq_f32_e64 s[24:25], s3, v34
	s_and_b64 s[18:19], s[18:19], s[26:27]
	s_or_b64 s[4:5], s[4:5], s[18:19]
	s_and_b64 s[20:21], s[20:21], s[26:27]
	s_or_b64 s[6:7], s[6:7], s[20:21]
	s_and_b64 s[22:23], s[22:23], s[26:27]
	s_or_b64 s[8:9], s[8:9], s[22:23]
	s_and_b64 s[24:25], s[24:25], s[26:27]
	s_or_b64 s[16:17], s[16:17], s[24:25]
	v_addc_co_u32_e64 v40, s[28:29], 0, v40, s[4:5]
	v_addc_co_u32_e64 v41, s[28:29], 0, v41, s[6:7]
	v_addc_co_u32_e64 v42, s[28:29], 0, v42, s[8:9]
	v_addc_co_u32_e64 v43, s[28:29], 0, v43, s[16:17]
	s_cmp_lt_u32 s30, 28
	s_cbranch_scc1 .Lnsa_rank_done
	v_readlane_b32 s0, v32, 28
	v_readlane_b32 s1, v33, 28
	v_readlane_b32 s2, v35, 28
	v_readlane_b32 s3, v34, 28
	s_lshl_b64 s[26:27], -1, 29
	v_cmp_gt_f32_e64 s[4:5], s0, v32
	v_cmp_gt_f32_e64 s[6:7], s1, v33
	v_cmp_gt_f32_e64 s[8:9], s2, v35
	v_cmp_gt_f32_e64 s[16:17], s3, v34
	v_cmp_eq_f32_e64 s[18:19], s0, v32
	v_cmp_eq_f32_e64 s[20:21], s1, v33
	v_cmp_eq_f32_e64 s[22:23], s2, v35
	v_cmp_eq_f32_e64 s[24:25], s3, v34
	s_and_b64 s[18:19], s[18:19], s[26:27]
	s_or_b64 s[4:5], s[4:5], s[18:19]
	s_and_b64 s[20:21], s[20:21], s[26:27]
	s_or_b64 s[6:7], s[6:7], s[20:21]
	s_and_b64 s[22:23], s[22:23], s[26:27]
	s_or_b64 s[8:9], s[8:9], s[22:23]
	s_and_b64 s[24:25], s[24:25], s[26:27]
	s_or_b64 s[16:17], s[16:17], s[24:25]
	v_addc_co_u32_e64 v40, s[28:29], 0, v40, s[4:5]
	v_addc_co_u32_e64 v41, s[28:29], 0, v41, s[6:7]
	v_addc_co_u32_e64 v42, s[28:29], 0, v42, s[8:9]
	v_addc_co_u32_e64 v43, s[28:29], 0, v43, s[16:17]
	v_readlane_b32 s0, v32, 29
	v_readlane_b32 s1, v33, 29
	v_readlane_b32 s2, v35, 29
	v_readlane_b32 s3, v34, 29
	s_lshl_b64 s[26:27], -1, 30
	v_cmp_gt_f32_e64 s[4:5], s0, v32
	v_cmp_gt_f32_e64 s[6:7], s1, v33
	v_cmp_gt_f32_e64 s[8:9], s2, v35
	v_cmp_gt_f32_e64 s[16:17], s3, v34
	v_cmp_eq_f32_e64 s[18:19], s0, v32
	v_cmp_eq_f32_e64 s[20:21], s1, v33
	v_cmp_eq_f32_e64 s[22:23], s2, v35
	v_cmp_eq_f32_e64 s[24:25], s3, v34
	s_and_b64 s[18:19], s[18:19], s[26:27]
	s_or_b64 s[4:5], s[4:5], s[18:19]
	s_and_b64 s[20:21], s[20:21], s[26:27]
	s_or_b64 s[6:7], s[6:7], s[20:21]
	s_and_b64 s[22:23], s[22:23], s[26:27]
	s_or_b64 s[8:9], s[8:9], s[22:23]
	s_and_b64 s[24:25], s[24:25], s[26:27]
	s_or_b64 s[16:17], s[16:17], s[24:25]
	v_addc_co_u32_e64 v40, s[28:29], 0, v40, s[4:5]
	v_addc_co_u32_e64 v41, s[28:29], 0, v41, s[6:7]
	v_addc_co_u32_e64 v42, s[28:29], 0, v42, s[8:9]
	v_addc_co_u32_e64 v43, s[28:29], 0, v43, s[16:17]
	v_readlane_b32 s0, v32, 30
	v_readlane_b32 s1, v33, 30
	v_readlane_b32 s2, v35, 30
	v_readlane_b32 s3, v34, 30
	s_lshl_b64 s[26:27], -1, 31
	v_cmp_gt_f32_e64 s[4:5], s0, v32
	v_cmp_gt_f32_e64 s[6:7], s1, v33
	v_cmp_gt_f32_e64 s[8:9], s2, v35
	v_cmp_gt_f32_e64 s[16:17], s3, v34
	v_cmp_eq_f32_e64 s[18:19], s0, v32
	v_cmp_eq_f32_e64 s[20:21], s1, v33
	v_cmp_eq_f32_e64 s[22:23], s2, v35
	v_cmp_eq_f32_e64 s[24:25], s3, v34
	s_and_b64 s[18:19], s[18:19], s[26:27]
	s_or_b64 s[4:5], s[4:5], s[18:19]
	s_and_b64 s[20:21], s[20:21], s[26:27]
	s_or_b64 s[6:7], s[6:7], s[20:21]
	s_and_b64 s[22:23], s[22:23], s[26:27]
	s_or_b64 s[8:9], s[8:9], s[22:23]
	s_and_b64 s[24:25], s[24:25], s[26:27]
	s_or_b64 s[16:17], s[16:17], s[24:25]
	v_addc_co_u32_e64 v40, s[28:29], 0, v40, s[4:5]
	v_addc_co_u32_e64 v41, s[28:29], 0, v41, s[6:7]
	v_addc_co_u32_e64 v42, s[28:29], 0, v42, s[8:9]
	v_addc_co_u32_e64 v43, s[28:29], 0, v43, s[16:17]
	v_readlane_b32 s0, v32, 31
	v_readlane_b32 s1, v33, 31
	v_readlane_b32 s2, v35, 31
	v_readlane_b32 s3, v34, 31
	s_lshl_b64 s[26:27], -1, 32
	v_cmp_gt_f32_e64 s[4:5], s0, v32
	v_cmp_gt_f32_e64 s[6:7], s1, v33
	v_cmp_gt_f32_e64 s[8:9], s2, v35
	v_cmp_gt_f32_e64 s[16:17], s3, v34
	v_cmp_eq_f32_e64 s[18:19], s0, v32
	v_cmp_eq_f32_e64 s[20:21], s1, v33
	v_cmp_eq_f32_e64 s[22:23], s2, v35
	v_cmp_eq_f32_e64 s[24:25], s3, v34
	s_and_b64 s[18:19], s[18:19], s[26:27]
	s_or_b64 s[4:5], s[4:5], s[18:19]
	s_and_b64 s[20:21], s[20:21], s[26:27]
	s_or_b64 s[6:7], s[6:7], s[20:21]
	s_and_b64 s[22:23], s[22:23], s[26:27]
	s_or_b64 s[8:9], s[8:9], s[22:23]
	s_and_b64 s[24:25], s[24:25], s[26:27]
	s_or_b64 s[16:17], s[16:17], s[24:25]
	v_addc_co_u32_e64 v40, s[28:29], 0, v40, s[4:5]
	v_addc_co_u32_e64 v41, s[28:29], 0, v41, s[6:7]
	v_addc_co_u32_e64 v42, s[28:29], 0, v42, s[8:9]
	v_addc_co_u32_e64 v43, s[28:29], 0, v43, s[16:17]
	s_cmp_lt_u32 s30, 32
	s_cbranch_scc1 .Lnsa_rank_done
	v_readlane_b32 s0, v32, 32
	v_readlane_b32 s1, v33, 32
	v_readlane_b32 s2, v35, 32
	v_readlane_b32 s3, v34, 32
	s_lshl_b64 s[26:27], -1, 33
	v_cmp_gt_f32_e64 s[4:5], s0, v32
	v_cmp_gt_f32_e64 s[6:7], s1, v33
	v_cmp_gt_f32_e64 s[8:9], s2, v35
	v_cmp_gt_f32_e64 s[16:17], s3, v34
	v_cmp_eq_f32_e64 s[18:19], s0, v32
	v_cmp_eq_f32_e64 s[20:21], s1, v33
	v_cmp_eq_f32_e64 s[22:23], s2, v35
	v_cmp_eq_f32_e64 s[24:25], s3, v34
	s_and_b64 s[18:19], s[18:19], s[26:27]
	s_or_b64 s[4:5], s[4:5], s[18:19]
	s_and_b64 s[20:21], s[20:21], s[26:27]
	s_or_b64 s[6:7], s[6:7], s[20:21]
	s_and_b64 s[22:23], s[22:23], s[26:27]
	s_or_b64 s[8:9], s[8:9], s[22:23]
	s_and_b64 s[24:25], s[24:25], s[26:27]
	s_or_b64 s[16:17], s[16:17], s[24:25]
	v_addc_co_u32_e64 v40, s[28:29], 0, v40, s[4:5]
	v_addc_co_u32_e64 v41, s[28:29], 0, v41, s[6:7]
	v_addc_co_u32_e64 v42, s[28:29], 0, v42, s[8:9]
	v_addc_co_u32_e64 v43, s[28:29], 0, v43, s[16:17]
	v_readlane_b32 s0, v32, 33
	v_readlane_b32 s1, v33, 33
	v_readlane_b32 s2, v35, 33
	v_readlane_b32 s3, v34, 33
	s_lshl_b64 s[26:27], -1, 34
	v_cmp_gt_f32_e64 s[4:5], s0, v32
	v_cmp_gt_f32_e64 s[6:7], s1, v33
	v_cmp_gt_f32_e64 s[8:9], s2, v35
	v_cmp_gt_f32_e64 s[16:17], s3, v34
	v_cmp_eq_f32_e64 s[18:19], s0, v32
	v_cmp_eq_f32_e64 s[20:21], s1, v33
	v_cmp_eq_f32_e64 s[22:23], s2, v35
	v_cmp_eq_f32_e64 s[24:25], s3, v34
	s_and_b64 s[18:19], s[18:19], s[26:27]
	s_or_b64 s[4:5], s[4:5], s[18:19]
	s_and_b64 s[20:21], s[20:21], s[26:27]
	s_or_b64 s[6:7], s[6:7], s[20:21]
	s_and_b64 s[22:23], s[22:23], s[26:27]
	s_or_b64 s[8:9], s[8:9], s[22:23]
	s_and_b64 s[24:25], s[24:25], s[26:27]
	s_or_b64 s[16:17], s[16:17], s[24:25]
	v_addc_co_u32_e64 v40, s[28:29], 0, v40, s[4:5]
	v_addc_co_u32_e64 v41, s[28:29], 0, v41, s[6:7]
	v_addc_co_u32_e64 v42, s[28:29], 0, v42, s[8:9]
	v_addc_co_u32_e64 v43, s[28:29], 0, v43, s[16:17]
	v_readlane_b32 s0, v32, 34
	v_readlane_b32 s1, v33, 34
	v_readlane_b32 s2, v35, 34
	v_readlane_b32 s3, v34, 34
	s_lshl_b64 s[26:27], -1, 35
	v_cmp_gt_f32_e64 s[4:5], s0, v32
	v_cmp_gt_f32_e64 s[6:7], s1, v33
	v_cmp_gt_f32_e64 s[8:9], s2, v35
	v_cmp_gt_f32_e64 s[16:17], s3, v34
	v_cmp_eq_f32_e64 s[18:19], s0, v32
	v_cmp_eq_f32_e64 s[20:21], s1, v33
	v_cmp_eq_f32_e64 s[22:23], s2, v35
	v_cmp_eq_f32_e64 s[24:25], s3, v34
	s_and_b64 s[18:19], s[18:19], s[26:27]
	s_or_b64 s[4:5], s[4:5], s[18:19]
	s_and_b64 s[20:21], s[20:21], s[26:27]
	s_or_b64 s[6:7], s[6:7], s[20:21]
	s_and_b64 s[22:23], s[22:23], s[26:27]
	s_or_b64 s[8:9], s[8:9], s[22:23]
	s_and_b64 s[24:25], s[24:25], s[26:27]
	s_or_b64 s[16:17], s[16:17], s[24:25]
	v_addc_co_u32_e64 v40, s[28:29], 0, v40, s[4:5]
	v_addc_co_u32_e64 v41, s[28:29], 0, v41, s[6:7]
	v_addc_co_u32_e64 v42, s[28:29], 0, v42, s[8:9]
	v_addc_co_u32_e64 v43, s[28:29], 0, v43, s[16:17]
	v_readlane_b32 s0, v32, 35
	v_readlane_b32 s1, v33, 35
	v_readlane_b32 s2, v35, 35
	v_readlane_b32 s3, v34, 35
	s_lshl_b64 s[26:27], -1, 36
	v_cmp_gt_f32_e64 s[4:5], s0, v32
	v_cmp_gt_f32_e64 s[6:7], s1, v33
	v_cmp_gt_f32_e64 s[8:9], s2, v35
	v_cmp_gt_f32_e64 s[16:17], s3, v34
	v_cmp_eq_f32_e64 s[18:19], s0, v32
	v_cmp_eq_f32_e64 s[20:21], s1, v33
	v_cmp_eq_f32_e64 s[22:23], s2, v35
	v_cmp_eq_f32_e64 s[24:25], s3, v34
	s_and_b64 s[18:19], s[18:19], s[26:27]
	s_or_b64 s[4:5], s[4:5], s[18:19]
	s_and_b64 s[20:21], s[20:21], s[26:27]
	s_or_b64 s[6:7], s[6:7], s[20:21]
	s_and_b64 s[22:23], s[22:23], s[26:27]
	s_or_b64 s[8:9], s[8:9], s[22:23]
	s_and_b64 s[24:25], s[24:25], s[26:27]
	s_or_b64 s[16:17], s[16:17], s[24:25]
	v_addc_co_u32_e64 v40, s[28:29], 0, v40, s[4:5]
	v_addc_co_u32_e64 v41, s[28:29], 0, v41, s[6:7]
	v_addc_co_u32_e64 v42, s[28:29], 0, v42, s[8:9]
	v_addc_co_u32_e64 v43, s[28:29], 0, v43, s[16:17]
	s_cmp_lt_u32 s30, 36
	s_cbranch_scc1 .Lnsa_rank_done
	v_readlane_b32 s0, v32, 36
	v_readlane_b32 s1, v33, 36
	v_readlane_b32 s2, v35, 36
	v_readlane_b32 s3, v34, 36
	s_lshl_b64 s[26:27], -1, 37
	v_cmp_gt_f32_e64 s[4:5], s0, v32
	v_cmp_gt_f32_e64 s[6:7], s1, v33
	v_cmp_gt_f32_e64 s[8:9], s2, v35
	v_cmp_gt_f32_e64 s[16:17], s3, v34
	v_cmp_eq_f32_e64 s[18:19], s0, v32
	v_cmp_eq_f32_e64 s[20:21], s1, v33
	v_cmp_eq_f32_e64 s[22:23], s2, v35
	v_cmp_eq_f32_e64 s[24:25], s3, v34
	s_and_b64 s[18:19], s[18:19], s[26:27]
	s_or_b64 s[4:5], s[4:5], s[18:19]
	s_and_b64 s[20:21], s[20:21], s[26:27]
	s_or_b64 s[6:7], s[6:7], s[20:21]
	s_and_b64 s[22:23], s[22:23], s[26:27]
	s_or_b64 s[8:9], s[8:9], s[22:23]
	s_and_b64 s[24:25], s[24:25], s[26:27]
	s_or_b64 s[16:17], s[16:17], s[24:25]
	v_addc_co_u32_e64 v40, s[28:29], 0, v40, s[4:5]
	v_addc_co_u32_e64 v41, s[28:29], 0, v41, s[6:7]
	v_addc_co_u32_e64 v42, s[28:29], 0, v42, s[8:9]
	v_addc_co_u32_e64 v43, s[28:29], 0, v43, s[16:17]
	v_readlane_b32 s0, v32, 37
	v_readlane_b32 s1, v33, 37
	v_readlane_b32 s2, v35, 37
	v_readlane_b32 s3, v34, 37
	s_lshl_b64 s[26:27], -1, 38
	v_cmp_gt_f32_e64 s[4:5], s0, v32
	v_cmp_gt_f32_e64 s[6:7], s1, v33
	v_cmp_gt_f32_e64 s[8:9], s2, v35
	v_cmp_gt_f32_e64 s[16:17], s3, v34
	v_cmp_eq_f32_e64 s[18:19], s0, v32
	v_cmp_eq_f32_e64 s[20:21], s1, v33
	v_cmp_eq_f32_e64 s[22:23], s2, v35
	v_cmp_eq_f32_e64 s[24:25], s3, v34
	s_and_b64 s[18:19], s[18:19], s[26:27]
	s_or_b64 s[4:5], s[4:5], s[18:19]
	s_and_b64 s[20:21], s[20:21], s[26:27]
	s_or_b64 s[6:7], s[6:7], s[20:21]
	s_and_b64 s[22:23], s[22:23], s[26:27]
	s_or_b64 s[8:9], s[8:9], s[22:23]
	s_and_b64 s[24:25], s[24:25], s[26:27]
	s_or_b64 s[16:17], s[16:17], s[24:25]
	v_addc_co_u32_e64 v40, s[28:29], 0, v40, s[4:5]
	v_addc_co_u32_e64 v41, s[28:29], 0, v41, s[6:7]
	v_addc_co_u32_e64 v42, s[28:29], 0, v42, s[8:9]
	v_addc_co_u32_e64 v43, s[28:29], 0, v43, s[16:17]
	v_readlane_b32 s0, v32, 38
	v_readlane_b32 s1, v33, 38
	v_readlane_b32 s2, v35, 38
	v_readlane_b32 s3, v34, 38
	s_lshl_b64 s[26:27], -1, 39
	v_cmp_gt_f32_e64 s[4:5], s0, v32
	v_cmp_gt_f32_e64 s[6:7], s1, v33
	v_cmp_gt_f32_e64 s[8:9], s2, v35
	v_cmp_gt_f32_e64 s[16:17], s3, v34
	v_cmp_eq_f32_e64 s[18:19], s0, v32
	v_cmp_eq_f32_e64 s[20:21], s1, v33
	v_cmp_eq_f32_e64 s[22:23], s2, v35
	v_cmp_eq_f32_e64 s[24:25], s3, v34
	s_and_b64 s[18:19], s[18:19], s[26:27]
	s_or_b64 s[4:5], s[4:5], s[18:19]
	s_and_b64 s[20:21], s[20:21], s[26:27]
	s_or_b64 s[6:7], s[6:7], s[20:21]
	s_and_b64 s[22:23], s[22:23], s[26:27]
	s_or_b64 s[8:9], s[8:9], s[22:23]
	s_and_b64 s[24:25], s[24:25], s[26:27]
	s_or_b64 s[16:17], s[16:17], s[24:25]
	v_addc_co_u32_e64 v40, s[28:29], 0, v40, s[4:5]
	v_addc_co_u32_e64 v41, s[28:29], 0, v41, s[6:7]
	v_addc_co_u32_e64 v42, s[28:29], 0, v42, s[8:9]
	v_addc_co_u32_e64 v43, s[28:29], 0, v43, s[16:17]
	v_readlane_b32 s0, v32, 39
	v_readlane_b32 s1, v33, 39
	v_readlane_b32 s2, v35, 39
	v_readlane_b32 s3, v34, 39
	s_lshl_b64 s[26:27], -1, 40
	v_cmp_gt_f32_e64 s[4:5], s0, v32
	v_cmp_gt_f32_e64 s[6:7], s1, v33
	v_cmp_gt_f32_e64 s[8:9], s2, v35
	v_cmp_gt_f32_e64 s[16:17], s3, v34
	v_cmp_eq_f32_e64 s[18:19], s0, v32
	v_cmp_eq_f32_e64 s[20:21], s1, v33
	v_cmp_eq_f32_e64 s[22:23], s2, v35
	v_cmp_eq_f32_e64 s[24:25], s3, v34
	s_and_b64 s[18:19], s[18:19], s[26:27]
	s_or_b64 s[4:5], s[4:5], s[18:19]
	s_and_b64 s[20:21], s[20:21], s[26:27]
	s_or_b64 s[6:7], s[6:7], s[20:21]
	s_and_b64 s[22:23], s[22:23], s[26:27]
	s_or_b64 s[8:9], s[8:9], s[22:23]
	s_and_b64 s[24:25], s[24:25], s[26:27]
	s_or_b64 s[16:17], s[16:17], s[24:25]
	v_addc_co_u32_e64 v40, s[28:29], 0, v40, s[4:5]
	v_addc_co_u32_e64 v41, s[28:29], 0, v41, s[6:7]
	v_addc_co_u32_e64 v42, s[28:29], 0, v42, s[8:9]
	v_addc_co_u32_e64 v43, s[28:29], 0, v43, s[16:17]
	s_cmp_lt_u32 s30, 40
	s_cbranch_scc1 .Lnsa_rank_done
	v_readlane_b32 s0, v32, 40
	v_readlane_b32 s1, v33, 40
	v_readlane_b32 s2, v35, 40
	v_readlane_b32 s3, v34, 40
	s_lshl_b64 s[26:27], -1, 41
	v_cmp_gt_f32_e64 s[4:5], s0, v32
	v_cmp_gt_f32_e64 s[6:7], s1, v33
	v_cmp_gt_f32_e64 s[8:9], s2, v35
	v_cmp_gt_f32_e64 s[16:17], s3, v34
	v_cmp_eq_f32_e64 s[18:19], s0, v32
	v_cmp_eq_f32_e64 s[20:21], s1, v33
	v_cmp_eq_f32_e64 s[22:23], s2, v35
	v_cmp_eq_f32_e64 s[24:25], s3, v34
	s_and_b64 s[18:19], s[18:19], s[26:27]
	s_or_b64 s[4:5], s[4:5], s[18:19]
	s_and_b64 s[20:21], s[20:21], s[26:27]
	s_or_b64 s[6:7], s[6:7], s[20:21]
	s_and_b64 s[22:23], s[22:23], s[26:27]
	s_or_b64 s[8:9], s[8:9], s[22:23]
	s_and_b64 s[24:25], s[24:25], s[26:27]
	s_or_b64 s[16:17], s[16:17], s[24:25]
	v_addc_co_u32_e64 v40, s[28:29], 0, v40, s[4:5]
	v_addc_co_u32_e64 v41, s[28:29], 0, v41, s[6:7]
	v_addc_co_u32_e64 v42, s[28:29], 0, v42, s[8:9]
	v_addc_co_u32_e64 v43, s[28:29], 0, v43, s[16:17]
	v_readlane_b32 s0, v32, 41
	v_readlane_b32 s1, v33, 41
	v_readlane_b32 s2, v35, 41
	v_readlane_b32 s3, v34, 41
	s_lshl_b64 s[26:27], -1, 42
	v_cmp_gt_f32_e64 s[4:5], s0, v32
	v_cmp_gt_f32_e64 s[6:7], s1, v33
	v_cmp_gt_f32_e64 s[8:9], s2, v35
	v_cmp_gt_f32_e64 s[16:17], s3, v34
	v_cmp_eq_f32_e64 s[18:19], s0, v32
	v_cmp_eq_f32_e64 s[20:21], s1, v33
	v_cmp_eq_f32_e64 s[22:23], s2, v35
	v_cmp_eq_f32_e64 s[24:25], s3, v34
	s_and_b64 s[18:19], s[18:19], s[26:27]
	s_or_b64 s[4:5], s[4:5], s[18:19]
	s_and_b64 s[20:21], s[20:21], s[26:27]
	s_or_b64 s[6:7], s[6:7], s[20:21]
	s_and_b64 s[22:23], s[22:23], s[26:27]
	s_or_b64 s[8:9], s[8:9], s[22:23]
	s_and_b64 s[24:25], s[24:25], s[26:27]
	s_or_b64 s[16:17], s[16:17], s[24:25]
	v_addc_co_u32_e64 v40, s[28:29], 0, v40, s[4:5]
	v_addc_co_u32_e64 v41, s[28:29], 0, v41, s[6:7]
	v_addc_co_u32_e64 v42, s[28:29], 0, v42, s[8:9]
	v_addc_co_u32_e64 v43, s[28:29], 0, v43, s[16:17]
	v_readlane_b32 s0, v32, 42
	v_readlane_b32 s1, v33, 42
	v_readlane_b32 s2, v35, 42
	v_readlane_b32 s3, v34, 42
	s_lshl_b64 s[26:27], -1, 43
	v_cmp_gt_f32_e64 s[4:5], s0, v32
	v_cmp_gt_f32_e64 s[6:7], s1, v33
	v_cmp_gt_f32_e64 s[8:9], s2, v35
	v_cmp_gt_f32_e64 s[16:17], s3, v34
	v_cmp_eq_f32_e64 s[18:19], s0, v32
	v_cmp_eq_f32_e64 s[20:21], s1, v33
	v_cmp_eq_f32_e64 s[22:23], s2, v35
	v_cmp_eq_f32_e64 s[24:25], s3, v34
	s_and_b64 s[18:19], s[18:19], s[26:27]
	s_or_b64 s[4:5], s[4:5], s[18:19]
	s_and_b64 s[20:21], s[20:21], s[26:27]
	s_or_b64 s[6:7], s[6:7], s[20:21]
	s_and_b64 s[22:23], s[22:23], s[26:27]
	s_or_b64 s[8:9], s[8:9], s[22:23]
	s_and_b64 s[24:25], s[24:25], s[26:27]
	s_or_b64 s[16:17], s[16:17], s[24:25]
	v_addc_co_u32_e64 v40, s[28:29], 0, v40, s[4:5]
	v_addc_co_u32_e64 v41, s[28:29], 0, v41, s[6:7]
	v_addc_co_u32_e64 v42, s[28:29], 0, v42, s[8:9]
	v_addc_co_u32_e64 v43, s[28:29], 0, v43, s[16:17]
	v_readlane_b32 s0, v32, 43
	v_readlane_b32 s1, v33, 43
	v_readlane_b32 s2, v35, 43
	v_readlane_b32 s3, v34, 43
	s_lshl_b64 s[26:27], -1, 44
	v_cmp_gt_f32_e64 s[4:5], s0, v32
	v_cmp_gt_f32_e64 s[6:7], s1, v33
	v_cmp_gt_f32_e64 s[8:9], s2, v35
	v_cmp_gt_f32_e64 s[16:17], s3, v34
	v_cmp_eq_f32_e64 s[18:19], s0, v32
	v_cmp_eq_f32_e64 s[20:21], s1, v33
	v_cmp_eq_f32_e64 s[22:23], s2, v35
	v_cmp_eq_f32_e64 s[24:25], s3, v34
	s_and_b64 s[18:19], s[18:19], s[26:27]
	s_or_b64 s[4:5], s[4:5], s[18:19]
	s_and_b64 s[20:21], s[20:21], s[26:27]
	s_or_b64 s[6:7], s[6:7], s[20:21]
	s_and_b64 s[22:23], s[22:23], s[26:27]
	s_or_b64 s[8:9], s[8:9], s[22:23]
	s_and_b64 s[24:25], s[24:25], s[26:27]
	s_or_b64 s[16:17], s[16:17], s[24:25]
	v_addc_co_u32_e64 v40, s[28:29], 0, v40, s[4:5]
	v_addc_co_u32_e64 v41, s[28:29], 0, v41, s[6:7]
	v_addc_co_u32_e64 v42, s[28:29], 0, v42, s[8:9]
	v_addc_co_u32_e64 v43, s[28:29], 0, v43, s[16:17]
	s_cmp_lt_u32 s30, 44
	s_cbranch_scc1 .Lnsa_rank_done
	v_readlane_b32 s0, v32, 44
	v_readlane_b32 s1, v33, 44
	v_readlane_b32 s2, v35, 44
	v_readlane_b32 s3, v34, 44
	s_lshl_b64 s[26:27], -1, 45
	v_cmp_gt_f32_e64 s[4:5], s0, v32
	v_cmp_gt_f32_e64 s[6:7], s1, v33
	v_cmp_gt_f32_e64 s[8:9], s2, v35
	v_cmp_gt_f32_e64 s[16:17], s3, v34
	v_cmp_eq_f32_e64 s[18:19], s0, v32
	v_cmp_eq_f32_e64 s[20:21], s1, v33
	v_cmp_eq_f32_e64 s[22:23], s2, v35
	v_cmp_eq_f32_e64 s[24:25], s3, v34
	s_and_b64 s[18:19], s[18:19], s[26:27]
	s_or_b64 s[4:5], s[4:5], s[18:19]
	s_and_b64 s[20:21], s[20:21], s[26:27]
	s_or_b64 s[6:7], s[6:7], s[20:21]
	s_and_b64 s[22:23], s[22:23], s[26:27]
	s_or_b64 s[8:9], s[8:9], s[22:23]
	s_and_b64 s[24:25], s[24:25], s[26:27]
	s_or_b64 s[16:17], s[16:17], s[24:25]
	v_addc_co_u32_e64 v40, s[28:29], 0, v40, s[4:5]
	v_addc_co_u32_e64 v41, s[28:29], 0, v41, s[6:7]
	v_addc_co_u32_e64 v42, s[28:29], 0, v42, s[8:9]
	v_addc_co_u32_e64 v43, s[28:29], 0, v43, s[16:17]
	v_readlane_b32 s0, v32, 45
	v_readlane_b32 s1, v33, 45
	v_readlane_b32 s2, v35, 45
	v_readlane_b32 s3, v34, 45
	s_lshl_b64 s[26:27], -1, 46
	v_cmp_gt_f32_e64 s[4:5], s0, v32
	v_cmp_gt_f32_e64 s[6:7], s1, v33
	v_cmp_gt_f32_e64 s[8:9], s2, v35
	v_cmp_gt_f32_e64 s[16:17], s3, v34
	v_cmp_eq_f32_e64 s[18:19], s0, v32
	v_cmp_eq_f32_e64 s[20:21], s1, v33
	v_cmp_eq_f32_e64 s[22:23], s2, v35
	v_cmp_eq_f32_e64 s[24:25], s3, v34
	s_and_b64 s[18:19], s[18:19], s[26:27]
	s_or_b64 s[4:5], s[4:5], s[18:19]
	s_and_b64 s[20:21], s[20:21], s[26:27]
	s_or_b64 s[6:7], s[6:7], s[20:21]
	s_and_b64 s[22:23], s[22:23], s[26:27]
	s_or_b64 s[8:9], s[8:9], s[22:23]
	s_and_b64 s[24:25], s[24:25], s[26:27]
	s_or_b64 s[16:17], s[16:17], s[24:25]
	v_addc_co_u32_e64 v40, s[28:29], 0, v40, s[4:5]
	v_addc_co_u32_e64 v41, s[28:29], 0, v41, s[6:7]
	v_addc_co_u32_e64 v42, s[28:29], 0, v42, s[8:9]
	v_addc_co_u32_e64 v43, s[28:29], 0, v43, s[16:17]
	v_readlane_b32 s0, v32, 46
	v_readlane_b32 s1, v33, 46
	v_readlane_b32 s2, v35, 46
	v_readlane_b32 s3, v34, 46
	s_lshl_b64 s[26:27], -1, 47
	v_cmp_gt_f32_e64 s[4:5], s0, v32
	v_cmp_gt_f32_e64 s[6:7], s1, v33
	v_cmp_gt_f32_e64 s[8:9], s2, v35
	v_cmp_gt_f32_e64 s[16:17], s3, v34
	v_cmp_eq_f32_e64 s[18:19], s0, v32
	v_cmp_eq_f32_e64 s[20:21], s1, v33
	v_cmp_eq_f32_e64 s[22:23], s2, v35
	v_cmp_eq_f32_e64 s[24:25], s3, v34
	s_and_b64 s[18:19], s[18:19], s[26:27]
	s_or_b64 s[4:5], s[4:5], s[18:19]
	s_and_b64 s[20:21], s[20:21], s[26:27]
	s_or_b64 s[6:7], s[6:7], s[20:21]
	s_and_b64 s[22:23], s[22:23], s[26:27]
	s_or_b64 s[8:9], s[8:9], s[22:23]
	s_and_b64 s[24:25], s[24:25], s[26:27]
	s_or_b64 s[16:17], s[16:17], s[24:25]
	v_addc_co_u32_e64 v40, s[28:29], 0, v40, s[4:5]
	v_addc_co_u32_e64 v41, s[28:29], 0, v41, s[6:7]
	v_addc_co_u32_e64 v42, s[28:29], 0, v42, s[8:9]
	v_addc_co_u32_e64 v43, s[28:29], 0, v43, s[16:17]
	v_readlane_b32 s0, v32, 47
	v_readlane_b32 s1, v33, 47
	v_readlane_b32 s2, v35, 47
	v_readlane_b32 s3, v34, 47
	s_lshl_b64 s[26:27], -1, 48
	v_cmp_gt_f32_e64 s[4:5], s0, v32
	v_cmp_gt_f32_e64 s[6:7], s1, v33
	v_cmp_gt_f32_e64 s[8:9], s2, v35
	v_cmp_gt_f32_e64 s[16:17], s3, v34
	v_cmp_eq_f32_e64 s[18:19], s0, v32
	v_cmp_eq_f32_e64 s[20:21], s1, v33
	v_cmp_eq_f32_e64 s[22:23], s2, v35
	v_cmp_eq_f32_e64 s[24:25], s3, v34
	s_and_b64 s[18:19], s[18:19], s[26:27]
	s_or_b64 s[4:5], s[4:5], s[18:19]
	s_and_b64 s[20:21], s[20:21], s[26:27]
	s_or_b64 s[6:7], s[6:7], s[20:21]
	s_and_b64 s[22:23], s[22:23], s[26:27]
	s_or_b64 s[8:9], s[8:9], s[22:23]
	s_and_b64 s[24:25], s[24:25], s[26:27]
	s_or_b64 s[16:17], s[16:17], s[24:25]
	v_addc_co_u32_e64 v40, s[28:29], 0, v40, s[4:5]
	v_addc_co_u32_e64 v41, s[28:29], 0, v41, s[6:7]
	v_addc_co_u32_e64 v42, s[28:29], 0, v42, s[8:9]
	v_addc_co_u32_e64 v43, s[28:29], 0, v43, s[16:17]
	s_cmp_lt_u32 s30, 48
	s_cbranch_scc1 .Lnsa_rank_done
	v_readlane_b32 s0, v32, 48
	v_readlane_b32 s1, v33, 48
	v_readlane_b32 s2, v35, 48
	v_readlane_b32 s3, v34, 48
	s_lshl_b64 s[26:27], -1, 49
	v_cmp_gt_f32_e64 s[4:5], s0, v32
	v_cmp_gt_f32_e64 s[6:7], s1, v33
	v_cmp_gt_f32_e64 s[8:9], s2, v35
	v_cmp_gt_f32_e64 s[16:17], s3, v34
	v_cmp_eq_f32_e64 s[18:19], s0, v32
	v_cmp_eq_f32_e64 s[20:21], s1, v33
	v_cmp_eq_f32_e64 s[22:23], s2, v35
	v_cmp_eq_f32_e64 s[24:25], s3, v34
	s_and_b64 s[18:19], s[18:19], s[26:27]
	s_or_b64 s[4:5], s[4:5], s[18:19]
	s_and_b64 s[20:21], s[20:21], s[26:27]
	s_or_b64 s[6:7], s[6:7], s[20:21]
	s_and_b64 s[22:23], s[22:23], s[26:27]
	s_or_b64 s[8:9], s[8:9], s[22:23]
	s_and_b64 s[24:25], s[24:25], s[26:27]
	s_or_b64 s[16:17], s[16:17], s[24:25]
	v_addc_co_u32_e64 v40, s[28:29], 0, v40, s[4:5]
	v_addc_co_u32_e64 v41, s[28:29], 0, v41, s[6:7]
	v_addc_co_u32_e64 v42, s[28:29], 0, v42, s[8:9]
	v_addc_co_u32_e64 v43, s[28:29], 0, v43, s[16:17]
	v_readlane_b32 s0, v32, 49
	v_readlane_b32 s1, v33, 49
	v_readlane_b32 s2, v35, 49
	v_readlane_b32 s3, v34, 49
	s_lshl_b64 s[26:27], -1, 50
	v_cmp_gt_f32_e64 s[4:5], s0, v32
	v_cmp_gt_f32_e64 s[6:7], s1, v33
	v_cmp_gt_f32_e64 s[8:9], s2, v35
	v_cmp_gt_f32_e64 s[16:17], s3, v34
	v_cmp_eq_f32_e64 s[18:19], s0, v32
	v_cmp_eq_f32_e64 s[20:21], s1, v33
	v_cmp_eq_f32_e64 s[22:23], s2, v35
	v_cmp_eq_f32_e64 s[24:25], s3, v34
	s_and_b64 s[18:19], s[18:19], s[26:27]
	s_or_b64 s[4:5], s[4:5], s[18:19]
	s_and_b64 s[20:21], s[20:21], s[26:27]
	s_or_b64 s[6:7], s[6:7], s[20:21]
	s_and_b64 s[22:23], s[22:23], s[26:27]
	s_or_b64 s[8:9], s[8:9], s[22:23]
	s_and_b64 s[24:25], s[24:25], s[26:27]
	s_or_b64 s[16:17], s[16:17], s[24:25]
	v_addc_co_u32_e64 v40, s[28:29], 0, v40, s[4:5]
	v_addc_co_u32_e64 v41, s[28:29], 0, v41, s[6:7]
	v_addc_co_u32_e64 v42, s[28:29], 0, v42, s[8:9]
	v_addc_co_u32_e64 v43, s[28:29], 0, v43, s[16:17]
	v_readlane_b32 s0, v32, 50
	v_readlane_b32 s1, v33, 50
	v_readlane_b32 s2, v35, 50
	v_readlane_b32 s3, v34, 50
	s_lshl_b64 s[26:27], -1, 51
	v_cmp_gt_f32_e64 s[4:5], s0, v32
	v_cmp_gt_f32_e64 s[6:7], s1, v33
	v_cmp_gt_f32_e64 s[8:9], s2, v35
	v_cmp_gt_f32_e64 s[16:17], s3, v34
	v_cmp_eq_f32_e64 s[18:19], s0, v32
	v_cmp_eq_f32_e64 s[20:21], s1, v33
	v_cmp_eq_f32_e64 s[22:23], s2, v35
	v_cmp_eq_f32_e64 s[24:25], s3, v34
	s_and_b64 s[18:19], s[18:19], s[26:27]
	s_or_b64 s[4:5], s[4:5], s[18:19]
	s_and_b64 s[20:21], s[20:21], s[26:27]
	s_or_b64 s[6:7], s[6:7], s[20:21]
	s_and_b64 s[22:23], s[22:23], s[26:27]
	s_or_b64 s[8:9], s[8:9], s[22:23]
	s_and_b64 s[24:25], s[24:25], s[26:27]
	s_or_b64 s[16:17], s[16:17], s[24:25]
	v_addc_co_u32_e64 v40, s[28:29], 0, v40, s[4:5]
	v_addc_co_u32_e64 v41, s[28:29], 0, v41, s[6:7]
	v_addc_co_u32_e64 v42, s[28:29], 0, v42, s[8:9]
	v_addc_co_u32_e64 v43, s[28:29], 0, v43, s[16:17]
	v_readlane_b32 s0, v32, 51
	v_readlane_b32 s1, v33, 51
	v_readlane_b32 s2, v35, 51
	v_readlane_b32 s3, v34, 51
	s_lshl_b64 s[26:27], -1, 52
	v_cmp_gt_f32_e64 s[4:5], s0, v32
	v_cmp_gt_f32_e64 s[6:7], s1, v33
	v_cmp_gt_f32_e64 s[8:9], s2, v35
	v_cmp_gt_f32_e64 s[16:17], s3, v34
	v_cmp_eq_f32_e64 s[18:19], s0, v32
	v_cmp_eq_f32_e64 s[20:21], s1, v33
	v_cmp_eq_f32_e64 s[22:23], s2, v35
	v_cmp_eq_f32_e64 s[24:25], s3, v34
	s_and_b64 s[18:19], s[18:19], s[26:27]
	s_or_b64 s[4:5], s[4:5], s[18:19]
	s_and_b64 s[20:21], s[20:21], s[26:27]
	s_or_b64 s[6:7], s[6:7], s[20:21]
	s_and_b64 s[22:23], s[22:23], s[26:27]
	s_or_b64 s[8:9], s[8:9], s[22:23]
	s_and_b64 s[24:25], s[24:25], s[26:27]
	s_or_b64 s[16:17], s[16:17], s[24:25]
	v_addc_co_u32_e64 v40, s[28:29], 0, v40, s[4:5]
	v_addc_co_u32_e64 v41, s[28:29], 0, v41, s[6:7]
	v_addc_co_u32_e64 v42, s[28:29], 0, v42, s[8:9]
	v_addc_co_u32_e64 v43, s[28:29], 0, v43, s[16:17]
	s_cmp_lt_u32 s30, 52
	s_cbranch_scc1 .Lnsa_rank_done
	v_readlane_b32 s0, v32, 52
	v_readlane_b32 s1, v33, 52
	v_readlane_b32 s2, v35, 52
	v_readlane_b32 s3, v34, 52
	s_lshl_b64 s[26:27], -1, 53
	v_cmp_gt_f32_e64 s[4:5], s0, v32
	v_cmp_gt_f32_e64 s[6:7], s1, v33
	v_cmp_gt_f32_e64 s[8:9], s2, v35
	v_cmp_gt_f32_e64 s[16:17], s3, v34
	v_cmp_eq_f32_e64 s[18:19], s0, v32
	v_cmp_eq_f32_e64 s[20:21], s1, v33
	v_cmp_eq_f32_e64 s[22:23], s2, v35
	v_cmp_eq_f32_e64 s[24:25], s3, v34
	s_and_b64 s[18:19], s[18:19], s[26:27]
	s_or_b64 s[4:5], s[4:5], s[18:19]
	s_and_b64 s[20:21], s[20:21], s[26:27]
	s_or_b64 s[6:7], s[6:7], s[20:21]
	s_and_b64 s[22:23], s[22:23], s[26:27]
	s_or_b64 s[8:9], s[8:9], s[22:23]
	s_and_b64 s[24:25], s[24:25], s[26:27]
	s_or_b64 s[16:17], s[16:17], s[24:25]
	v_addc_co_u32_e64 v40, s[28:29], 0, v40, s[4:5]
	v_addc_co_u32_e64 v41, s[28:29], 0, v41, s[6:7]
	v_addc_co_u32_e64 v42, s[28:29], 0, v42, s[8:9]
	v_addc_co_u32_e64 v43, s[28:29], 0, v43, s[16:17]
	v_readlane_b32 s0, v32, 53
	v_readlane_b32 s1, v33, 53
	v_readlane_b32 s2, v35, 53
	v_readlane_b32 s3, v34, 53
	s_lshl_b64 s[26:27], -1, 54
	v_cmp_gt_f32_e64 s[4:5], s0, v32
	v_cmp_gt_f32_e64 s[6:7], s1, v33
	v_cmp_gt_f32_e64 s[8:9], s2, v35
	v_cmp_gt_f32_e64 s[16:17], s3, v34
	v_cmp_eq_f32_e64 s[18:19], s0, v32
	v_cmp_eq_f32_e64 s[20:21], s1, v33
	v_cmp_eq_f32_e64 s[22:23], s2, v35
	v_cmp_eq_f32_e64 s[24:25], s3, v34
	s_and_b64 s[18:19], s[18:19], s[26:27]
	s_or_b64 s[4:5], s[4:5], s[18:19]
	s_and_b64 s[20:21], s[20:21], s[26:27]
	s_or_b64 s[6:7], s[6:7], s[20:21]
	s_and_b64 s[22:23], s[22:23], s[26:27]
	s_or_b64 s[8:9], s[8:9], s[22:23]
	s_and_b64 s[24:25], s[24:25], s[26:27]
	s_or_b64 s[16:17], s[16:17], s[24:25]
	v_addc_co_u32_e64 v40, s[28:29], 0, v40, s[4:5]
	v_addc_co_u32_e64 v41, s[28:29], 0, v41, s[6:7]
	v_addc_co_u32_e64 v42, s[28:29], 0, v42, s[8:9]
	v_addc_co_u32_e64 v43, s[28:29], 0, v43, s[16:17]
	v_readlane_b32 s0, v32, 54
	v_readlane_b32 s1, v33, 54
	v_readlane_b32 s2, v35, 54
	v_readlane_b32 s3, v34, 54
	s_lshl_b64 s[26:27], -1, 55
	v_cmp_gt_f32_e64 s[4:5], s0, v32
	v_cmp_gt_f32_e64 s[6:7], s1, v33
	v_cmp_gt_f32_e64 s[8:9], s2, v35
	v_cmp_gt_f32_e64 s[16:17], s3, v34
	v_cmp_eq_f32_e64 s[18:19], s0, v32
	v_cmp_eq_f32_e64 s[20:21], s1, v33
	v_cmp_eq_f32_e64 s[22:23], s2, v35
	v_cmp_eq_f32_e64 s[24:25], s3, v34
	s_and_b64 s[18:19], s[18:19], s[26:27]
	s_or_b64 s[4:5], s[4:5], s[18:19]
	s_and_b64 s[20:21], s[20:21], s[26:27]
	s_or_b64 s[6:7], s[6:7], s[20:21]
	s_and_b64 s[22:23], s[22:23], s[26:27]
	s_or_b64 s[8:9], s[8:9], s[22:23]
	s_and_b64 s[24:25], s[24:25], s[26:27]
	s_or_b64 s[16:17], s[16:17], s[24:25]
	v_addc_co_u32_e64 v40, s[28:29], 0, v40, s[4:5]
	v_addc_co_u32_e64 v41, s[28:29], 0, v41, s[6:7]
	v_addc_co_u32_e64 v42, s[28:29], 0, v42, s[8:9]
	v_addc_co_u32_e64 v43, s[28:29], 0, v43, s[16:17]
	v_readlane_b32 s0, v32, 55
	v_readlane_b32 s1, v33, 55
	v_readlane_b32 s2, v35, 55
	v_readlane_b32 s3, v34, 55
	s_lshl_b64 s[26:27], -1, 56
	v_cmp_gt_f32_e64 s[4:5], s0, v32
	v_cmp_gt_f32_e64 s[6:7], s1, v33
	v_cmp_gt_f32_e64 s[8:9], s2, v35
	v_cmp_gt_f32_e64 s[16:17], s3, v34
	v_cmp_eq_f32_e64 s[18:19], s0, v32
	v_cmp_eq_f32_e64 s[20:21], s1, v33
	v_cmp_eq_f32_e64 s[22:23], s2, v35
	v_cmp_eq_f32_e64 s[24:25], s3, v34
	s_and_b64 s[18:19], s[18:19], s[26:27]
	s_or_b64 s[4:5], s[4:5], s[18:19]
	s_and_b64 s[20:21], s[20:21], s[26:27]
	s_or_b64 s[6:7], s[6:7], s[20:21]
	s_and_b64 s[22:23], s[22:23], s[26:27]
	s_or_b64 s[8:9], s[8:9], s[22:23]
	s_and_b64 s[24:25], s[24:25], s[26:27]
	s_or_b64 s[16:17], s[16:17], s[24:25]
	v_addc_co_u32_e64 v40, s[28:29], 0, v40, s[4:5]
	v_addc_co_u32_e64 v41, s[28:29], 0, v41, s[6:7]
	v_addc_co_u32_e64 v42, s[28:29], 0, v42, s[8:9]
	v_addc_co_u32_e64 v43, s[28:29], 0, v43, s[16:17]
	s_cmp_lt_u32 s30, 56
	s_cbranch_scc1 .Lnsa_rank_done
	v_readlane_b32 s0, v32, 56
	v_readlane_b32 s1, v33, 56
	v_readlane_b32 s2, v35, 56
	v_readlane_b32 s3, v34, 56
	s_lshl_b64 s[26:27], -1, 57
	v_cmp_gt_f32_e64 s[4:5], s0, v32
	v_cmp_gt_f32_e64 s[6:7], s1, v33
	v_cmp_gt_f32_e64 s[8:9], s2, v35
	v_cmp_gt_f32_e64 s[16:17], s3, v34
	v_cmp_eq_f32_e64 s[18:19], s0, v32
	v_cmp_eq_f32_e64 s[20:21], s1, v33
	v_cmp_eq_f32_e64 s[22:23], s2, v35
	v_cmp_eq_f32_e64 s[24:25], s3, v34
	s_and_b64 s[18:19], s[18:19], s[26:27]
	s_or_b64 s[4:5], s[4:5], s[18:19]
	s_and_b64 s[20:21], s[20:21], s[26:27]
	s_or_b64 s[6:7], s[6:7], s[20:21]
	s_and_b64 s[22:23], s[22:23], s[26:27]
	s_or_b64 s[8:9], s[8:9], s[22:23]
	s_and_b64 s[24:25], s[24:25], s[26:27]
	s_or_b64 s[16:17], s[16:17], s[24:25]
	v_addc_co_u32_e64 v40, s[28:29], 0, v40, s[4:5]
	v_addc_co_u32_e64 v41, s[28:29], 0, v41, s[6:7]
	v_addc_co_u32_e64 v42, s[28:29], 0, v42, s[8:9]
	v_addc_co_u32_e64 v43, s[28:29], 0, v43, s[16:17]
	v_readlane_b32 s0, v32, 57
	v_readlane_b32 s1, v33, 57
	v_readlane_b32 s2, v35, 57
	v_readlane_b32 s3, v34, 57
	s_lshl_b64 s[26:27], -1, 58
	v_cmp_gt_f32_e64 s[4:5], s0, v32
	v_cmp_gt_f32_e64 s[6:7], s1, v33
	v_cmp_gt_f32_e64 s[8:9], s2, v35
	v_cmp_gt_f32_e64 s[16:17], s3, v34
	v_cmp_eq_f32_e64 s[18:19], s0, v32
	v_cmp_eq_f32_e64 s[20:21], s1, v33
	v_cmp_eq_f32_e64 s[22:23], s2, v35
	v_cmp_eq_f32_e64 s[24:25], s3, v34
	s_and_b64 s[18:19], s[18:19], s[26:27]
	s_or_b64 s[4:5], s[4:5], s[18:19]
	s_and_b64 s[20:21], s[20:21], s[26:27]
	s_or_b64 s[6:7], s[6:7], s[20:21]
	s_and_b64 s[22:23], s[22:23], s[26:27]
	s_or_b64 s[8:9], s[8:9], s[22:23]
	s_and_b64 s[24:25], s[24:25], s[26:27]
	s_or_b64 s[16:17], s[16:17], s[24:25]
	v_addc_co_u32_e64 v40, s[28:29], 0, v40, s[4:5]
	v_addc_co_u32_e64 v41, s[28:29], 0, v41, s[6:7]
	v_addc_co_u32_e64 v42, s[28:29], 0, v42, s[8:9]
	v_addc_co_u32_e64 v43, s[28:29], 0, v43, s[16:17]
	v_readlane_b32 s0, v32, 58
	v_readlane_b32 s1, v33, 58
	v_readlane_b32 s2, v35, 58
	v_readlane_b32 s3, v34, 58
	s_lshl_b64 s[26:27], -1, 59
	v_cmp_gt_f32_e64 s[4:5], s0, v32
	v_cmp_gt_f32_e64 s[6:7], s1, v33
	v_cmp_gt_f32_e64 s[8:9], s2, v35
	v_cmp_gt_f32_e64 s[16:17], s3, v34
	v_cmp_eq_f32_e64 s[18:19], s0, v32
	v_cmp_eq_f32_e64 s[20:21], s1, v33
	v_cmp_eq_f32_e64 s[22:23], s2, v35
	v_cmp_eq_f32_e64 s[24:25], s3, v34
	s_and_b64 s[18:19], s[18:19], s[26:27]
	s_or_b64 s[4:5], s[4:5], s[18:19]
	s_and_b64 s[20:21], s[20:21], s[26:27]
	s_or_b64 s[6:7], s[6:7], s[20:21]
	s_and_b64 s[22:23], s[22:23], s[26:27]
	s_or_b64 s[8:9], s[8:9], s[22:23]
	s_and_b64 s[24:25], s[24:25], s[26:27]
	s_or_b64 s[16:17], s[16:17], s[24:25]
	v_addc_co_u32_e64 v40, s[28:29], 0, v40, s[4:5]
	v_addc_co_u32_e64 v41, s[28:29], 0, v41, s[6:7]
	v_addc_co_u32_e64 v42, s[28:29], 0, v42, s[8:9]
	v_addc_co_u32_e64 v43, s[28:29], 0, v43, s[16:17]
	v_readlane_b32 s0, v32, 59
	v_readlane_b32 s1, v33, 59
	v_readlane_b32 s2, v35, 59
	v_readlane_b32 s3, v34, 59
	s_lshl_b64 s[26:27], -1, 60
	v_cmp_gt_f32_e64 s[4:5], s0, v32
	v_cmp_gt_f32_e64 s[6:7], s1, v33
	v_cmp_gt_f32_e64 s[8:9], s2, v35
	v_cmp_gt_f32_e64 s[16:17], s3, v34
	v_cmp_eq_f32_e64 s[18:19], s0, v32
	v_cmp_eq_f32_e64 s[20:21], s1, v33
	v_cmp_eq_f32_e64 s[22:23], s2, v35
	v_cmp_eq_f32_e64 s[24:25], s3, v34
	s_and_b64 s[18:19], s[18:19], s[26:27]
	s_or_b64 s[4:5], s[4:5], s[18:19]
	s_and_b64 s[20:21], s[20:21], s[26:27]
	s_or_b64 s[6:7], s[6:7], s[20:21]
	s_and_b64 s[22:23], s[22:23], s[26:27]
	s_or_b64 s[8:9], s[8:9], s[22:23]
	s_and_b64 s[24:25], s[24:25], s[26:27]
	s_or_b64 s[16:17], s[16:17], s[24:25]
	v_addc_co_u32_e64 v40, s[28:29], 0, v40, s[4:5]
	v_addc_co_u32_e64 v41, s[28:29], 0, v41, s[6:7]
	v_addc_co_u32_e64 v42, s[28:29], 0, v42, s[8:9]
	v_addc_co_u32_e64 v43, s[28:29], 0, v43, s[16:17]
	s_cmp_lt_u32 s30, 60
	s_cbranch_scc1 .Lnsa_rank_done
	v_readlane_b32 s0, v32, 60
	v_readlane_b32 s1, v33, 60
	v_readlane_b32 s2, v35, 60
	v_readlane_b32 s3, v34, 60
	s_lshl_b64 s[26:27], -1, 61
	v_cmp_gt_f32_e64 s[4:5], s0, v32
	v_cmp_gt_f32_e64 s[6:7], s1, v33
	v_cmp_gt_f32_e64 s[8:9], s2, v35
	v_cmp_gt_f32_e64 s[16:17], s3, v34
	v_cmp_eq_f32_e64 s[18:19], s0, v32
	v_cmp_eq_f32_e64 s[20:21], s1, v33
	v_cmp_eq_f32_e64 s[22:23], s2, v35
	v_cmp_eq_f32_e64 s[24:25], s3, v34
	s_and_b64 s[18:19], s[18:19], s[26:27]
	s_or_b64 s[4:5], s[4:5], s[18:19]
	s_and_b64 s[20:21], s[20:21], s[26:27]
	s_or_b64 s[6:7], s[6:7], s[20:21]
	s_and_b64 s[22:23], s[22:23], s[26:27]
	s_or_b64 s[8:9], s[8:9], s[22:23]
	s_and_b64 s[24:25], s[24:25], s[26:27]
	s_or_b64 s[16:17], s[16:17], s[24:25]
	v_addc_co_u32_e64 v40, s[28:29], 0, v40, s[4:5]
	v_addc_co_u32_e64 v41, s[28:29], 0, v41, s[6:7]
	v_addc_co_u32_e64 v42, s[28:29], 0, v42, s[8:9]
	v_addc_co_u32_e64 v43, s[28:29], 0, v43, s[16:17]
	v_readlane_b32 s0, v32, 61
	v_readlane_b32 s1, v33, 61
	v_readlane_b32 s2, v35, 61
	v_readlane_b32 s3, v34, 61
	s_lshl_b64 s[26:27], -1, 62
	v_cmp_gt_f32_e64 s[4:5], s0, v32
	v_cmp_gt_f32_e64 s[6:7], s1, v33
	v_cmp_gt_f32_e64 s[8:9], s2, v35
	v_cmp_gt_f32_e64 s[16:17], s3, v34
	v_cmp_eq_f32_e64 s[18:19], s0, v32
	v_cmp_eq_f32_e64 s[20:21], s1, v33
	v_cmp_eq_f32_e64 s[22:23], s2, v35
	v_cmp_eq_f32_e64 s[24:25], s3, v34
	s_and_b64 s[18:19], s[18:19], s[26:27]
	s_or_b64 s[4:5], s[4:5], s[18:19]
	s_and_b64 s[20:21], s[20:21], s[26:27]
	s_or_b64 s[6:7], s[6:7], s[20:21]
	s_and_b64 s[22:23], s[22:23], s[26:27]
	s_or_b64 s[8:9], s[8:9], s[22:23]
	s_and_b64 s[24:25], s[24:25], s[26:27]
	s_or_b64 s[16:17], s[16:17], s[24:25]
	v_addc_co_u32_e64 v40, s[28:29], 0, v40, s[4:5]
	v_addc_co_u32_e64 v41, s[28:29], 0, v41, s[6:7]
	v_addc_co_u32_e64 v42, s[28:29], 0, v42, s[8:9]
	v_addc_co_u32_e64 v43, s[28:29], 0, v43, s[16:17]
	v_readlane_b32 s0, v32, 62
	v_readlane_b32 s1, v33, 62
	v_readlane_b32 s2, v35, 62
	v_readlane_b32 s3, v34, 62
	s_lshl_b64 s[26:27], -1, 63
	v_cmp_gt_f32_e64 s[4:5], s0, v32
	v_cmp_gt_f32_e64 s[6:7], s1, v33
	v_cmp_gt_f32_e64 s[8:9], s2, v35
	v_cmp_gt_f32_e64 s[16:17], s3, v34
	v_cmp_eq_f32_e64 s[18:19], s0, v32
	v_cmp_eq_f32_e64 s[20:21], s1, v33
	v_cmp_eq_f32_e64 s[22:23], s2, v35
	v_cmp_eq_f32_e64 s[24:25], s3, v34
	s_and_b64 s[18:19], s[18:19], s[26:27]
	s_or_b64 s[4:5], s[4:5], s[18:19]
	s_and_b64 s[20:21], s[20:21], s[26:27]
	s_or_b64 s[6:7], s[6:7], s[20:21]
	s_and_b64 s[22:23], s[22:23], s[26:27]
	s_or_b64 s[8:9], s[8:9], s[22:23]
	s_and_b64 s[24:25], s[24:25], s[26:27]
	s_or_b64 s[16:17], s[16:17], s[24:25]
	v_addc_co_u32_e64 v40, s[28:29], 0, v40, s[4:5]
	v_addc_co_u32_e64 v41, s[28:29], 0, v41, s[6:7]
	v_addc_co_u32_e64 v42, s[28:29], 0, v42, s[8:9]
	v_addc_co_u32_e64 v43, s[28:29], 0, v43, s[16:17]
	v_readlane_b32 s0, v32, 63
	v_readlane_b32 s1, v33, 63
	v_readlane_b32 s2, v35, 63
	v_readlane_b32 s3, v34, 63
	v_cmp_gt_f32_e64 s[4:5], s0, v32
	v_cmp_gt_f32_e64 s[6:7], s1, v33
	v_cmp_gt_f32_e64 s[8:9], s2, v35
	v_cmp_gt_f32_e64 s[16:17], s3, v34
	v_addc_co_u32_e64 v40, s[28:29], 0, v40, s[4:5]
	v_addc_co_u32_e64 v41, s[28:29], 0, v41, s[6:7]
	v_addc_co_u32_e64 v42, s[28:29], 0, v42, s[8:9]
	v_addc_co_u32_e64 v43, s[28:29], 0, v43, s[16:17]
.Lnsa_rank_done:
	v_cmp_gt_u32_e64 s[8:9], 16, v40
	v_cmp_gt_u32_e64 s[6:7], 16, v42
	v_cmp_gt_u32_e64 s[4:5], 16, v43
	v_cmp_eq_u32_e64 s[0:1], 0, v113
	v_cmp_gt_u32_e32 vcc, 16, v41
	s_and_saveexec_b64 s[2:3], s[0:1]
	s_cbranch_execz .LBB0_581
	s_lshl_b32 s0, s13, 3
	v_readlane_b32 s13, v254, 9
	s_lshl_b32 s1, s12, 3
	s_lshl_b32 s12, s15, 3
	s_add_i32 s12, s13, s12
	s_add_i32 s1, s13, s1
	v_mov_b32_e32 v32, s8
	v_mov_b32_e32 v33, s9
	v_mov_b32_e32 v34, vcc_lo
	v_mov_b32_e32 v35, vcc_hi
	v_mov_b32_e32 v40, s12
	s_add_i32 s0, s13, s0
	ds_write_b128 v40, v[32:35]
	v_mov_b32_e32 v32, s1
	v_mov_b64_e32 v[34:35], s[6:7]
	ds_write_b64 v32, v[34:35]
	v_mov_b32_e32 v32, s0
	v_mov_b64_e32 v[34:35], s[4:5]
	ds_write_b64 v32, v[34:35]
